# speedup vs baseline: 1.0138x; 1.0077x over previous
.LBB0_579:
	s_ashr_i32 s4, s0, 6
	s_mul_hi_i32 s5, s4, 0x55555556
	s_lshr_b32 s6, s5, 31
	s_add_i32 s5, s5, s6
	s_mul_i32 s5, s5, 3
	s_sub_i32 s4, s4, s5
	s_mul_hi_i32 s5, s0, 0x2aaaaaab
	s_lshr_b32 s6, s5, 31
	s_ashr_i32 s5, s5, 5
	s_and_b32 s7, s0, 15
	s_add_i32 s6, s5, s6
	s_lshl_b32 s5, s4, 1
	s_lshr_b32 s22, s7, s5
	s_lshl_b32 s8, -1, s5
	s_andn2_b32 s13, s7, s8
	v_sub_co_u32_e64 v0, s[8:9], s22, 1
	s_ashr_i32 s7, s6, 31
	v_readfirstlane_b32 s10, v0
	s_lshl_b64 s[6:7], s[6:7], 11
	s_ashr_i32 s11, s10, 31
	s_add_i32 s12, s5, 7
	s_bfe_u32 s1, s0, 0x20004
	s_lshl_b64 s[10:11], s[10:11], s12
	s_or_b32 s6, s6, s13
	s_add_u32 s10, s6, s10
	s_addc_u32 s11, s7, s11
	s_lshl_b64 s[10:11], s[10:11], 11
	s_add_u32 s10, s60, s10
	s_addc_u32 s11, s61, s11
	s_lshl_b32 s13, s1, 8
	s_add_u32 s16, s10, s13
	v_mov_b32_e32 v14, v190
	s_addc_u32 s17, s11, 0
	v_mov_b32_e32 v115, v190
	s_and_b64 s[8:9], s[8:9], exec
	s_cselect_b32 s11, 0x80, 0
	v_and_b32_e32 v16, 15, v115
	v_ashrrev_i32_e32 v12, 4, v115
	v_lshlrev_b32_e32 v128, 4, v16
	v_lshl_add_u64 v[10:11], s[16:17], 0, v[128:129]
	v_cmp_le_i32_e32 vcc, s11, v12
	v_mov_b32_e32 v0, 0
	v_mov_b32_e32 v2, 0
	v_mov_b32_e32 v3, 0
	v_mov_b32_e32 v4, 0
	v_mov_b32_e32 v5, 0
	v_mov_b32_e32 v6, 0
	v_mov_b32_e32 v7, 0
	v_mov_b32_e32 v8, 0
	v_mov_b32_e32 v9, 0
	s_add_i32 s13, s5, 10
	v_mov_b32_e32 v22, 0
	v_mov_b32_e32 v23, 0
	v_mov_b32_e32 v24, 0
	v_mov_b32_e32 v25, 0
	v_mov_b32_e32 v26, 0
	v_mov_b32_e32 v27, 0
	v_mov_b32_e32 v28, 0
	v_mov_b32_e32 v29, 0
	v_mov_b32_e32 v30, 0
	v_mov_b32_e32 v31, 0
	v_mov_b32_e32 v32, 0
	v_mov_b32_e32 v33, 0
	v_mov_b32_e32 v34, 0
	v_mov_b32_e32 v35, 0
	v_mov_b32_e32 v36, 0
	v_mov_b32_e32 v37, 0
	v_mov_b32_e32 v38, 0
	v_mov_b32_e32 v39, 0
	v_mov_b32_e32 v40, 0
	v_mov_b32_e32 v41, 0
	v_mov_b32_e32 v42, 0
	v_mov_b32_e32 v43, 0
	v_mov_b32_e32 v44, 0
	v_mov_b32_e32 v45, 0
	v_mov_b32_e32 v46, 0
	v_mov_b32_e32 v47, 0
	v_mov_b32_e32 v48, 0
	v_mov_b32_e32 v49, 0
	v_mov_b32_e32 v50, 0
	v_mov_b32_e32 v51, 0
	v_mov_b32_e32 v52, 0
	v_mov_b32_e32 v53, 0
	v_mov_b32_e32 v54, 0
	v_mov_b32_e32 v55, 0
	v_mov_b32_e32 v56, 0
	v_mov_b32_e32 v57, 0
	v_mov_b32_e32 v58, 0
	v_mov_b32_e32 v59, 0
	v_mov_b32_e32 v60, 0
	v_mov_b32_e32 v61, 0
	v_mov_b32_e32 v62, 0
	v_mov_b32_e32 v63, 0
	v_mov_b32_e32 v64, 0
	v_mov_b32_e32 v65, 0
	v_mov_b32_e32 v66, 0
	v_mov_b32_e32 v67, 0
	v_mov_b32_e32 v68, 0
	v_mov_b32_e32 v69, 0
	v_mov_b32_e32 v70, 0
	v_mov_b32_e32 v71, 0
	v_mov_b32_e32 v72, 0
	v_mov_b32_e32 v73, 0
	v_mov_b32_e32 v74, 0
	v_mov_b32_e32 v75, 0
	v_mov_b32_e32 v76, 0
	v_mov_b32_e32 v77, 0
	v_mov_b32_e32 v78, 0
	v_mov_b32_e32 v79, 0
	v_mov_b32_e32 v80, 0
	v_mov_b32_e32 v81, 0
	v_mov_b32_e32 v82, 0
	v_mov_b32_e32 v83, 0
	v_mov_b32_e32 v84, 0
	v_mov_b32_e32 v85, 0
	v_mov_b32_e32 v88, v12
	v_mov_b32_e32 v89, v129
	v_cmp_le_i32_e32 vcc, s11, v88
	s_and_saveexec_b64 s[8:9], vcc
	v_lshlrev_b64 v[86:87], s13, v[88:89]
	v_lshl_add_u64 v[86:87], v[86:87], 1, v[10:11]
	global_load_dwordx4 v[22:25], v[86:87], off
	global_load_dwordx4 v[26:29], v[86:87], off offset:1024
	s_or_b64 exec, exec, s[8:9]
	v_add_u32_e32 v88, 32, v12
	v_mov_b32_e32 v89, v129
	v_cmp_le_i32_e32 vcc, s11, v88
	s_and_saveexec_b64 s[8:9], vcc
	v_lshlrev_b64 v[86:87], s13, v[88:89]
	v_lshl_add_u64 v[86:87], v[86:87], 1, v[10:11]
	global_load_dwordx4 v[30:33], v[86:87], off
	global_load_dwordx4 v[34:37], v[86:87], off offset:1024
	s_or_b64 exec, exec, s[8:9]
	v_add_u32_e32 v88, 64, v12
	v_mov_b32_e32 v89, v129
	v_cmp_le_i32_e32 vcc, s11, v88
	s_and_saveexec_b64 s[8:9], vcc
	v_lshlrev_b64 v[86:87], s13, v[88:89]
	v_lshl_add_u64 v[86:87], v[86:87], 1, v[10:11]
	global_load_dwordx4 v[38:41], v[86:87], off
	global_load_dwordx4 v[42:45], v[86:87], off offset:1024
	s_or_b64 exec, exec, s[8:9]
	v_add_u32_e32 v88, 96, v12
	v_mov_b32_e32 v89, v129
	v_cmp_le_i32_e32 vcc, s11, v88
	s_and_saveexec_b64 s[8:9], vcc
	v_lshlrev_b64 v[86:87], s13, v[88:89]
	v_lshl_add_u64 v[86:87], v[86:87], 1, v[10:11]
	global_load_dwordx4 v[46:49], v[86:87], off
	global_load_dwordx4 v[50:53], v[86:87], off offset:1024
	s_or_b64 exec, exec, s[8:9]
	v_add_u32_e32 v88, 128, v12
	v_mov_b32_e32 v89, v129
	v_cmp_le_i32_e32 vcc, s11, v88
	s_and_saveexec_b64 s[8:9], vcc
	v_lshlrev_b64 v[86:87], s13, v[88:89]
	v_lshl_add_u64 v[86:87], v[86:87], 1, v[10:11]
	global_load_dwordx4 v[54:57], v[86:87], off
	global_load_dwordx4 v[58:61], v[86:87], off offset:1024
	s_or_b64 exec, exec, s[8:9]
	v_add_u32_e32 v88, 160, v12
	v_mov_b32_e32 v89, v129
	v_cmp_le_i32_e32 vcc, s11, v88
	s_and_saveexec_b64 s[8:9], vcc
	v_lshlrev_b64 v[86:87], s13, v[88:89]
	v_lshl_add_u64 v[86:87], v[86:87], 1, v[10:11]
	global_load_dwordx4 v[62:65], v[86:87], off
	global_load_dwordx4 v[66:69], v[86:87], off offset:1024
	s_or_b64 exec, exec, s[8:9]
	v_add_u32_e32 v88, 192, v12
	v_mov_b32_e32 v89, v129
	v_cmp_le_i32_e32 vcc, s11, v88
	s_and_saveexec_b64 s[8:9], vcc
	v_lshlrev_b64 v[86:87], s13, v[88:89]
	v_lshl_add_u64 v[86:87], v[86:87], 1, v[10:11]
	global_load_dwordx4 v[70:73], v[86:87], off
	global_load_dwordx4 v[74:77], v[86:87], off offset:1024
	s_or_b64 exec, exec, s[8:9]
	v_add_u32_e32 v88, 224, v12
	v_mov_b32_e32 v89, v129
	v_cmp_le_i32_e32 vcc, s11, v88
	s_and_saveexec_b64 s[8:9], vcc
	v_lshlrev_b64 v[86:87], s13, v[88:89]
	v_lshl_add_u64 v[86:87], v[86:87], 1, v[10:11]
	global_load_dwordx4 v[78:81], v[86:87], off
	global_load_dwordx4 v[82:85], v[86:87], off offset:1024
	s_or_b64 exec, exec, s[8:9]
	s_barrier
	v_xor_b32_e32 v1, v12, v115
	v_lshlrev_b32_e32 v1, 4, v1
	v_and_b32_e32 v1, 0xf0, v1
	v_add_u32_e32 v13, 0, v1
	v_lshrrev_b32_e32 v1, 1, v16
	v_lshlrev_b32_e32 v15, 1, v12
	v_bitop3_b32 v1, v15, v1, 6 bitop3:0x6c
	v_lshlrev_b32_e32 v15, 4, v115
	v_lshlrev_b32_e32 v1, 5, v1
	v_and_b32_e32 v15, 16, v15
	s_add_i32 s10, 0, 0x10000
	v_add3_u32 v15, s10, v1, v15
	v_lshlrev_b32_e32 v1, 8, v12
	v_add_u32_e32 v17, v13, v1
	v_add_u32_e32 v1, v15, v1
	v_add_u32_e32 v128, 32, v12
	s_waitcnt vmcnt(15)
	ds_write_b128 v17, v[22:25]
	s_waitcnt vmcnt(14)
	ds_write_b128 v1, v[26:29]
	v_cmp_le_i32_e32 vcc, s11, v128
	v_mov_b32_e32 v2, 0
	v_mov_b32_e32 v3, 0
	v_mov_b32_e32 v4, 0
	v_mov_b32_e32 v5, 0
	v_mov_b32_e32 v6, 0
	v_mov_b32_e32 v7, 0
	v_mov_b32_e32 v8, 0
	v_mov_b32_e32 v9, 0
	v_lshlrev_b32_e32 v1, 8, v128
	v_add_u32_e32 v17, v13, v1
	v_add_u32_e32 v1, v15, v1
	v_add_u32_e32 v128, 64, v12
	s_waitcnt vmcnt(13)
	ds_write_b128 v17, v[30:33]
	s_waitcnt vmcnt(12)
	ds_write_b128 v1, v[34:37]
	v_cmp_le_i32_e32 vcc, s11, v128
	v_mov_b32_e32 v1, 0
	v_mov_b32_e32 v2, 0
	v_mov_b32_e32 v3, 0
	v_mov_b32_e32 v4, 0
	v_mov_b32_e32 v5, 0
	v_mov_b32_e32 v6, 0
	v_mov_b32_e32 v7, 0
	v_lshlrev_b32_e32 v8, 8, v128
	v_add_u32_e32 v9, v13, v8
	s_waitcnt vmcnt(11)
	ds_write_b128 v9, v[38:41]
	v_add_u32_e32 v4, v15, v8
	v_add_u32_e32 v128, 0x60, v12
	s_waitcnt vmcnt(10)
	ds_write_b128 v4, v[42:45]
	v_cmp_le_i32_e32 vcc, s11, v128
	v_mov_b32_e32 v0, 0
	v_mov_b32_e32 v2, 0
	v_mov_b32_e32 v3, 0
	v_mov_b32_e32 v4, 0
	v_mov_b32_e32 v5, 0
	v_mov_b32_e32 v6, 0
	v_mov_b32_e32 v7, 0
	v_mov_b32_e32 v8, 0
	v_mov_b32_e32 v9, 0
	v_lshlrev_b32_e32 v1, 8, v128
	v_add_u32_e32 v17, v13, v1
	v_add_u32_e32 v1, v15, v1
	v_add_u32_e32 v128, 0x80, v12
	s_waitcnt vmcnt(9)
	ds_write_b128 v17, v[46:49]
	s_waitcnt vmcnt(8)
	ds_write_b128 v1, v[50:53]
	v_cmp_le_i32_e32 vcc, s11, v128
	v_mov_b32_e32 v1, 0
	v_mov_b32_e32 v2, 0
	v_mov_b32_e32 v3, 0
	v_mov_b32_e32 v4, 0
	v_mov_b32_e32 v5, 0
	v_mov_b32_e32 v6, 0
	v_mov_b32_e32 v7, 0
	v_lshlrev_b32_e32 v8, 8, v128
	v_add_u32_e32 v9, v13, v8
	s_waitcnt vmcnt(7)
	ds_write_b128 v9, v[54:57]
	v_add_u32_e32 v4, v15, v8
	v_add_u32_e32 v128, 0xa0, v12
	s_waitcnt vmcnt(6)
	ds_write_b128 v4, v[58:61]
	v_cmp_le_i32_e32 vcc, s11, v128
	v_mov_b32_e32 v0, 0
	v_mov_b32_e32 v2, 0
	v_mov_b32_e32 v3, 0
	v_mov_b32_e32 v4, 0
	v_mov_b32_e32 v5, 0
	v_mov_b32_e32 v6, 0
	v_mov_b32_e32 v7, 0
	v_mov_b32_e32 v8, 0
	v_mov_b32_e32 v9, 0
	v_lshlrev_b32_e32 v1, 8, v128
	v_add_u32_e32 v17, v13, v1
	v_add_u32_e32 v1, v15, v1
	v_add_u32_e32 v128, 0xc0, v12
	s_waitcnt vmcnt(5)
	ds_write_b128 v17, v[62:65]
	s_waitcnt vmcnt(4)
	ds_write_b128 v1, v[66:69]
	v_cmp_le_i32_e32 vcc, s11, v128
	v_mov_b32_e32 v1, 0
	v_mov_b32_e32 v2, 0
	v_mov_b32_e32 v3, 0
	v_mov_b32_e32 v4, 0
	v_mov_b32_e32 v5, 0
	v_mov_b32_e32 v6, 0
	v_mov_b32_e32 v7, 0
	v_lshlrev_b32_e32 v8, 8, v128
	v_add_u32_e32 v9, v13, v8
	s_waitcnt vmcnt(3)
	ds_write_b128 v9, v[70:73]
	v_add_u32_e32 v4, v15, v8
	v_add_u32_e32 v8, 0xe0, v12
	s_waitcnt vmcnt(2)
	ds_write_b128 v4, v[74:77]
	v_cmp_le_i32_e32 vcc, s11, v8
	v_mov_b32_e32 v0, 0
	v_mov_b32_e32 v1, 0
	v_mov_b32_e32 v2, 0
	v_mov_b32_e32 v3, 0
	v_mov_b32_e32 v4, 0
	v_mov_b32_e32 v5, 0
	v_mov_b32_e32 v6, 0
	v_mov_b32_e32 v7, 0
	s_lshl_b32 s1, s1, 1
	v_readlane_b32 s8, v240, 42
	s_add_i32 s1, s1, s8
	v_readlane_b32 s8, v240, 44
	v_mov_b64_e32 v[18:19], s[66:67]
	v_lshlrev_b32_e32 v8, 8, v8
	v_and_or_b32 v128, v14, 31, s8
	s_lshl_b64 s[8:9], s[22:23], s12
	s_add_u32 s6, s6, s8
	v_lshlrev_b64 v[10:11], s5, v[128:129]
	s_addc_u32 s7, s7, s9
	v_lshl_add_u64 v[10:11], s[6:7], 0, v[10:11]
	s_movk_i32 s5, 0x1800
	v_mad_u64_u32 v[18:19], s[6:7], v10, s5, v[18:19]
	v_mov_b32_e32 v12, v19
	v_mad_u64_u32 v[20:21], s[6:7], v11, s5, v[12:13]
	s_ashr_i32 s5, s4, 31
	s_lshl_b32 s6, s4, 10
	s_lshl_b64 s[4:5], s[4:5], 13
	v_lshl_add_u64 v[108:109], v[10:11], 0, s[4:5]
	v_lshlrev_b64 v[10:11], 11, v[108:109]
	s_lshl_b32 s22, s1, 8
	v_lshl_add_u64 v[10:11], s[90:91], 0, v[10:11]
	v_mov_b32_e32 v19, v20
	s_ashr_i32 s7, s6, 31
	v_lshl_add_u64 v[110:111], v[10:11], 0, s[22:23]
	v_add_u32_e32 v10, v13, v8
	v_lshl_add_u64 v[18:19], s[6:7], 1, v[18:19]
	s_waitcnt vmcnt(1)
	ds_write_b128 v10, v[78:81]
	v_add_u32_e32 v4, v15, v8
	v_bfe_u32 v114, v115, 5, 1
	v_lshl_add_u64 v[18:19], v[18:19], 0, s[22:23]
	s_waitcnt vmcnt(0)
	ds_write_b128 v4, v[82:85]
	v_lshlrev_b32_e32 v0, 4, v114
	v_mov_b32_e32 v1, v129
	v_lshl_add_u64 v[0:1], v[18:19], 0, v[0:1]
	global_load_dwordx4 v[64:67], v[0:1], off
	global_load_dwordx4 v[104:107], v[0:1], off offset:32
	global_load_dwordx4 v[100:103], v[0:1], off offset:64
	global_load_dwordx4 v[96:99], v[0:1], off offset:96
	global_load_dwordx4 v[92:95], v[0:1], off offset:128
	global_load_dwordx4 v[88:91], v[0:1], off offset:160
	global_load_dwordx4 v[84:87], v[0:1], off offset:192
	global_load_dwordx4 v[80:83], v[0:1], off offset:224
	v_lshlrev_b32_e32 v0, 8, v115
	v_lshrrev_b32_e32 v9, 5, v115
	v_readfirstlane_b32 s4, v115
	v_and_b32_e32 v0, 0x1f00, v0
	s_bfe_u32 s4, s4, 0x20006
	v_add_u32_e32 v68, 0, v0
	v_bitop3_b32 v0, v9, v16, 1 bitop3:0x6c
	v_lshlrev_b32_e32 v69, 4, v0
	v_lshl_add_u32 v17, s4, 13, v68
	v_add_u32_e32 v0, v17, v69
	s_waitcnt lgkmcnt(0)
	s_barrier
	ds_read_b128 v[0:3], v0
	v_bitop3_b32 v18, v114, v16, 2 bitop3:0x36
	v_lshlrev_b32_e32 v122, 4, v18
	v_add_u32_e32 v18, v17, v122
	ds_read_b128 v[18:21], v18
	s_add_i32 s7, s4, 3
	v_lshl_add_u32 v74, s7, 13, v68
	v_add_u32_e32 v70, v74, v122
	s_add_i32 s5, s4, 1
	s_add_i32 s6, s4, 2
	s_or_b32 s8, s4, 4
	v_lshl_add_u32 v36, s5, 13, v68
	v_lshl_add_u32 v52, s6, 13, v68
	v_lshl_add_u32 v126, s8, 13, v68
	v_add_u32_e32 v32, v36, v122
	v_add_u32_e32 v48, v52, v122
	v_add_u32_e32 v122, v126, v122
	v_add_u32_e32 v68, v126, v69
	v_lshlrev_b32_e32 v112, 3, v114
	v_mov_b32_e32 v113, v129
	s_waitcnt vmcnt(7) lgkmcnt(1)
	v_mfma_f32_32x32x16_bf16 v[0:15], v[0:3], v[64:67], 0
	ds_read_b128 v[70:73], v70
	ds_read_b128 v[122:125], v122
	ds_read_b128 v[32:35], v32
	ds_read_b128 v[48:51], v48
	s_waitcnt vmcnt(6) lgkmcnt(4)
	v_mfma_f32_32x32x16_bf16 v[0:15], v[18:21], v[104:107], v[0:15]
	v_bitop3_b32 v18, v114, v16, 4 bitop3:0x36
	v_lshlrev_b32_e32 v121, 4, v18
	v_add_u32_e32 v18, v17, v121
	ds_read_b128 v[18:21], v18
	s_waitcnt vmcnt(5) lgkmcnt(0)
	v_mfma_f32_32x32x16_bf16 v[0:15], v[18:21], v[100:103], v[0:15]
	v_bitop3_b32 v18, v114, v16, 6 bitop3:0x36
	v_lshlrev_b32_e32 v120, 4, v18
	v_add_u32_e32 v18, v17, v120
	ds_read_b128 v[18:21], v18
	s_waitcnt vmcnt(4) lgkmcnt(0)
	v_mfma_f32_32x32x16_bf16 v[0:15], v[18:21], v[96:99], v[0:15]
	v_bitop3_b32 v18, v114, v16, 8 bitop3:0x36
	v_lshlrev_b32_e32 v119, 4, v18
	v_add_u32_e32 v18, v17, v119
	ds_read_b128 v[18:21], v18
	s_waitcnt vmcnt(3) lgkmcnt(0)
	v_mfma_f32_32x32x16_bf16 v[0:15], v[18:21], v[92:95], v[0:15]
	v_bitop3_b32 v18, v114, v16, 10 bitop3:0x36
	v_lshlrev_b32_e32 v118, 4, v18
	v_add_u32_e32 v18, v17, v118
	ds_read_b128 v[18:21], v18
	s_waitcnt vmcnt(2) lgkmcnt(0)
	v_mfma_f32_32x32x16_bf16 v[0:15], v[18:21], v[88:91], v[0:15]
	v_bitop3_b32 v18, v114, v16, 12 bitop3:0x36
	v_lshlrev_b32_e32 v117, 4, v18
	v_add_u32_e32 v18, v17, v117
	ds_read_b128 v[18:21], v18
	v_bitop3_b32 v16, v114, v16, 14 bitop3:0x36
	v_lshlrev_b32_e32 v116, 4, v16
	v_add_u32_e32 v16, v17, v116
	s_waitcnt vmcnt(1) lgkmcnt(0)
	v_mfma_f32_32x32x16_bf16 v[0:15], v[18:21], v[84:87], v[0:15]
	ds_read_b128 v[16:19], v16
	s_waitcnt vmcnt(0) lgkmcnt(0)
	v_mfma_f32_32x32x16_bf16 v[0:15], v[16:19], v[80:83], v[0:15]
	v_add_u32_e32 v16, v36, v69
	ds_read_b128 v[16:19], v16
	s_waitcnt lgkmcnt(0)
	v_mfma_f32_32x32x16_bf16 v[16:31], v[16:19], v[64:67], 0
	v_mfma_f32_32x32x16_bf16 v[16:31], v[32:35], v[104:107], v[16:31]
	v_add_u32_e32 v32, v36, v121
	ds_read_b128 v[32:35], v32
	s_waitcnt lgkmcnt(0)
	v_mfma_f32_32x32x16_bf16 v[16:31], v[32:35], v[100:103], v[16:31]
	v_add_u32_e32 v32, v36, v120
	ds_read_b128 v[32:35], v32
	s_waitcnt lgkmcnt(0)
	v_mfma_f32_32x32x16_bf16 v[16:31], v[32:35], v[96:99], v[16:31]
	v_add_u32_e32 v32, v36, v119
	ds_read_b128 v[32:35], v32
	s_waitcnt lgkmcnt(0)
	v_mfma_f32_32x32x16_bf16 v[16:31], v[32:35], v[92:95], v[16:31]
	v_add_u32_e32 v32, v36, v118
	ds_read_b128 v[32:35], v32
	s_waitcnt lgkmcnt(0)
	v_mfma_f32_32x32x16_bf16 v[16:31], v[32:35], v[88:91], v[16:31]
	v_add_u32_e32 v32, v36, v117
	ds_read_b128 v[32:35], v32
	s_waitcnt lgkmcnt(0)
	v_mfma_f32_32x32x16_bf16 v[16:31], v[32:35], v[84:87], v[16:31]
	v_add_u32_e32 v32, v36, v116
	ds_read_b128 v[32:35], v32
	s_waitcnt lgkmcnt(0)
	v_mfma_f32_32x32x16_bf16 v[16:31], v[32:35], v[80:83], v[16:31]
	v_add_u32_e32 v32, v52, v69
	ds_read_b128 v[32:35], v32
	s_waitcnt lgkmcnt(0)
	v_mfma_f32_32x32x16_bf16 v[32:47], v[32:35], v[64:67], 0
	v_mfma_f32_32x32x16_bf16 v[32:47], v[48:51], v[104:107], v[32:47]
	v_add_u32_e32 v48, v52, v121
	ds_read_b128 v[48:51], v48
	s_waitcnt lgkmcnt(0)
	v_mfma_f32_32x32x16_bf16 v[32:47], v[48:51], v[100:103], v[32:47]
	v_add_u32_e32 v48, v52, v120
	ds_read_b128 v[48:51], v48
	s_waitcnt lgkmcnt(0)
	v_mfma_f32_32x32x16_bf16 v[32:47], v[48:51], v[96:99], v[32:47]
	v_add_u32_e32 v48, v52, v119
	ds_read_b128 v[48:51], v48
	s_waitcnt lgkmcnt(0)
	v_mfma_f32_32x32x16_bf16 v[32:47], v[48:51], v[92:95], v[32:47]
	v_add_u32_e32 v48, v52, v118
	ds_read_b128 v[48:51], v48
	s_waitcnt lgkmcnt(0)
	v_mfma_f32_32x32x16_bf16 v[32:47], v[48:51], v[88:91], v[32:47]
	v_add_u32_e32 v48, v52, v117
	ds_read_b128 v[48:51], v48
	s_waitcnt lgkmcnt(0)
	v_mfma_f32_32x32x16_bf16 v[32:47], v[48:51], v[84:87], v[32:47]
	v_add_u32_e32 v48, v52, v116
	ds_read_b128 v[48:51], v48
	s_waitcnt lgkmcnt(0)
	v_mfma_f32_32x32x16_bf16 v[32:47], v[48:51], v[80:83], v[32:47]
	v_add_u32_e32 v48, v74, v69
	ds_read_b128 v[48:51], v48
	s_waitcnt lgkmcnt(0)
	v_mfma_f32_32x32x16_bf16 v[48:63], v[48:51], v[64:67], 0
	v_mfma_f32_32x32x16_bf16 v[48:63], v[70:73], v[104:107], v[48:63]
	v_add_u32_e32 v70, v74, v121
	ds_read_b128 v[70:73], v70
	s_waitcnt lgkmcnt(0)
	v_mfma_f32_32x32x16_bf16 v[48:63], v[70:73], v[100:103], v[48:63]
	v_add_u32_e32 v70, v74, v120
	ds_read_b128 v[70:73], v70
	s_waitcnt lgkmcnt(0)
	v_mfma_f32_32x32x16_bf16 v[48:63], v[70:73], v[96:99], v[48:63]
	v_add_u32_e32 v70, v74, v119
	ds_read_b128 v[70:73], v70
	s_waitcnt lgkmcnt(0)
	v_mfma_f32_32x32x16_bf16 v[48:63], v[70:73], v[92:95], v[48:63]
	v_add_u32_e32 v70, v74, v118
	ds_read_b128 v[70:73], v70
	s_waitcnt lgkmcnt(0)
	v_mfma_f32_32x32x16_bf16 v[48:63], v[70:73], v[88:91], v[48:63]
	v_add_u32_e32 v70, v74, v117
	ds_read_b128 v[70:73], v70
	s_waitcnt lgkmcnt(0)
	v_mfma_f32_32x32x16_bf16 v[48:63], v[70:73], v[84:87], v[48:63]
	v_add_u32_e32 v70, v74, v116
	ds_read_b128 v[70:73], v70
	s_waitcnt lgkmcnt(0)
	v_mfma_f32_32x32x16_bf16 v[48:63], v[70:73], v[80:83], v[48:63]
	ds_read_b128 v[68:71], v68
	s_waitcnt lgkmcnt(0)
	v_mfma_f32_32x32x16_bf16 v[64:79], v[68:71], v[64:67], 0
	v_mfma_f32_32x32x16_bf16 v[64:79], v[122:125], v[104:107], v[64:79]
	v_add_u32_e32 v104, v126, v121
	ds_read_b128 v[104:107], v104
	s_waitcnt lgkmcnt(0)
	v_mfma_f32_32x32x16_bf16 v[64:79], v[104:107], v[100:103], v[64:79]
	v_add_u32_e32 v100, v126, v120
	ds_read_b128 v[100:103], v100
	s_waitcnt lgkmcnt(0)
	v_mfma_f32_32x32x16_bf16 v[64:79], v[100:103], v[96:99], v[64:79]
	v_add_u32_e32 v96, v126, v119
	ds_read_b128 v[96:99], v96
	v_lshlrev_b32_e32 v100, 2, v114
	v_lshl_or_b32 v107, s4, 5, v100
	v_max_u32_e32 v101, s11, v128
	v_cmp_le_u32_e32 vcc, v101, v107
	v_or_b32_e32 v103, 0x80, v128
	s_waitcnt lgkmcnt(0)
	v_mfma_f32_32x32x16_bf16 v[64:79], v[96:99], v[92:95], v[64:79]
	v_add_u32_e32 v92, v126, v118
	ds_read_b128 v[92:95], v92
	v_cndmask_b32_e32 v0, v218, v0, vcc
	v_lshl_or_b32 v106, s5, 5, v100
	v_cmp_le_u32_e64 s[38:39], v101, v106
	s_mov_b32 s4, 0xff800000
	v_lshl_or_b32 v105, s6, 5, v100
	s_waitcnt lgkmcnt(0)
	v_mfma_f32_32x32x16_bf16 v[64:79], v[92:95], v[88:91], v[64:79]
	v_add_u32_e32 v88, v126, v117
	ds_read_b128 v[88:91], v88
	v_lshl_or_b32 v102, s7, 5, v100
	s_waitcnt lgkmcnt(0)
	v_mfma_f32_32x32x16_bf16 v[64:79], v[88:91], v[84:87], v[64:79]
	v_add_u32_e32 v84, v126, v116
	ds_read_b128 v[84:87], v84
	s_waitcnt lgkmcnt(0)
	v_mfma_f32_32x32x16_bf16 v[64:79], v[84:87], v[80:83], v[64:79]
	v_or_b32_e32 v80, 1, v107
	v_cmp_le_u32_e32 vcc, v101, v80
	v_or_b32_e32 v81, 2, v107
	s_nop 0
	v_cndmask_b32_e32 v1, v218, v1, vcc
	v_cmp_le_u32_e32 vcc, v101, v81
	v_or_b32_e32 v81, 3, v107
	v_max3_f32 v80, v0, s4, v1
	v_cndmask_b32_e32 v2, v218, v2, vcc
	v_cmp_le_u32_e32 vcc, v101, v81
	v_or_b32_e32 v81, 8, v107
	s_movk_i32 s4, 0x80
	v_cndmask_b32_e32 v3, v218, v3, vcc
	v_cmp_le_u32_e32 vcc, v101, v81
	v_max3_f32 v80, v80, v2, v3
	s_nop 0
	v_cndmask_b32_e32 v104, v218, v4, vcc
	v_or_b32_e32 v4, 9, v107
	v_cmp_le_u32_e32 vcc, v101, v4
	s_nop 1
	v_cndmask_b32_e32 v116, v218, v5, vcc
	v_or_b32_e32 v5, 10, v107
	v_cmp_le_u32_e32 vcc, v101, v5
	v_or_b32_e32 v5, 11, v107
	v_max3_f32 v4, v80, v104, v116
	v_cndmask_b32_e32 v117, v218, v6, vcc
	v_cmp_le_u32_e32 vcc, v101, v5
	v_or_b32_e32 v5, 16, v107
	v_or_b32_e32 v6, 3, v105
	v_cndmask_b32_e32 v118, v218, v7, vcc
	v_cmp_le_u32_e32 vcc, v101, v5
	v_or_b32_e32 v5, 17, v107
	v_max3_f32 v4, v4, v117, v118
	v_cndmask_b32_e32 v98, v218, v8, vcc
	v_cmp_le_u32_e32 vcc, v101, v5
	v_or_b32_e32 v5, 18, v107
	s_nop 0
	v_cndmask_b32_e32 v99, v218, v9, vcc
	v_cmp_le_u32_e32 vcc, v101, v5
	v_or_b32_e32 v5, 19, v107
	v_max3_f32 v4, v4, v98, v99
	v_cndmask_b32_e32 v96, v218, v10, vcc
	v_cmp_le_u32_e32 vcc, v101, v5
	v_or_b32_e32 v5, 24, v107
	v_or_b32_e32 v9, 9, v105
	v_cndmask_b32_e32 v97, v218, v11, vcc
	v_cmp_le_u32_e32 vcc, v101, v5
	v_or_b32_e32 v5, 25, v107
	v_max3_f32 v4, v4, v96, v97
	v_cndmask_b32_e32 v94, v218, v12, vcc
	v_cmp_le_u32_e32 vcc, v101, v5
	v_or_b32_e32 v5, 26, v107
	v_or_b32_e32 v12, 11, v105
	v_cndmask_b32_e32 v95, v218, v13, vcc
	v_cmp_le_u32_e32 vcc, v101, v5
	v_or_b32_e32 v5, 27, v107
	v_max3_f32 v4, v4, v94, v95
	v_cndmask_b32_e32 v92, v218, v14, vcc
	v_cmp_le_u32_e32 vcc, v101, v5
	v_or_b32_e32 v5, 1, v106
	v_or_b32_e32 v13, 17, v105
	v_cndmask_b32_e32 v93, v218, v15, vcc
	v_cmp_le_u32_e32 vcc, v106, v103
	s_and_b64 vcc, s[38:39], vcc
	v_cmp_le_u32_e64 s[38:39], v101, v5
	v_cndmask_b32_e32 v88, v218, v16, vcc
	v_cmp_lt_u32_e32 vcc, v106, v103
	s_and_b64 vcc, s[38:39], vcc
	v_or_b32_e32 v5, 2, v106
	v_cndmask_b32_e32 v85, v218, v17, vcc
	v_cmp_le_u32_e32 vcc, v5, v103
	v_cmp_le_u32_e64 s[38:39], v101, v5
	s_and_b64 vcc, s[38:39], vcc
	v_or_b32_e32 v5, 3, v106
	v_cndmask_b32_e32 v89, v218, v18, vcc
	v_cmp_le_u32_e32 vcc, v5, v103
	v_cmp_le_u32_e64 s[38:39], v101, v5
	s_and_b64 vcc, s[38:39], vcc
	v_or_b32_e32 v5, 8, v106
	v_cndmask_b32_e32 v91, v218, v19, vcc
	v_cmp_le_u32_e32 vcc, v5, v103
	v_cmp_le_u32_e64 s[38:39], v101, v5
	s_and_b64 vcc, s[38:39], vcc
	v_or_b32_e32 v5, 9, v106
	v_cndmask_b32_e32 v86, v218, v20, vcc
	v_cmp_le_u32_e32 vcc, v5, v103
	v_cmp_le_u32_e64 s[38:39], v101, v5
	s_and_b64 vcc, s[38:39], vcc
	v_or_b32_e32 v5, 10, v106
	v_cndmask_b32_e32 v84, v218, v21, vcc
	v_cmp_le_u32_e32 vcc, v5, v103
	v_cmp_le_u32_e64 s[38:39], v101, v5
	s_and_b64 vcc, s[38:39], vcc
	v_or_b32_e32 v5, 11, v106
	v_cndmask_b32_e32 v87, v218, v22, vcc
	v_cmp_le_u32_e32 vcc, v5, v103
	v_cmp_le_u32_e64 s[38:39], v101, v5
	s_and_b64 vcc, s[38:39], vcc
	v_or_b32_e32 v5, 16, v106
	v_cndmask_b32_e32 v90, v218, v23, vcc
	v_cmp_le_u32_e32 vcc, v5, v103
	v_cmp_le_u32_e64 s[38:39], v101, v5
	s_and_b64 vcc, s[38:39], vcc
	v_or_b32_e32 v5, 17, v106
	v_cndmask_b32_e32 v81, v218, v24, vcc
	v_cmp_le_u32_e32 vcc, v5, v103
	v_cmp_le_u32_e64 s[38:39], v101, v5
	s_and_b64 vcc, s[38:39], vcc
	v_or_b32_e32 v5, 18, v106
	v_cndmask_b32_e32 v80, v218, v25, vcc
	v_cmp_le_u32_e32 vcc, v5, v103
	v_cmp_le_u32_e64 s[38:39], v101, v5
	s_and_b64 vcc, s[38:39], vcc
	v_or_b32_e32 v5, 19, v106
	v_cndmask_b32_e32 v82, v218, v26, vcc
	v_cmp_le_u32_e32 vcc, v5, v103
	v_cmp_le_u32_e64 s[38:39], v101, v5
	s_and_b64 vcc, s[38:39], vcc
	v_or_b32_e32 v5, 24, v106
	v_cndmask_b32_e32 v83, v218, v27, vcc
	v_cmp_le_u32_e32 vcc, v5, v103
	v_cmp_le_u32_e64 s[38:39], v101, v5
	v_max3_f32 v4, v4, v92, v93
	s_and_b64 vcc, s[38:39], vcc
	v_or_b32_e32 v5, 25, v106
	v_max3_f32 v4, v4, v88, v85
	v_cndmask_b32_e32 v28, v218, v28, vcc
	v_cmp_le_u32_e32 vcc, v5, v103
	v_cmp_le_u32_e64 s[38:39], v101, v5
	v_max3_f32 v4, v4, v89, v91
	s_and_b64 vcc, s[38:39], vcc
	v_or_b32_e32 v5, 26, v106
	v_max3_f32 v4, v4, v86, v84
	v_cndmask_b32_e32 v26, v218, v29, vcc
	v_cmp_le_u32_e32 vcc, v5, v103
	v_cmp_le_u32_e64 s[38:39], v101, v5
	v_max3_f32 v4, v4, v87, v90
	s_and_b64 vcc, s[38:39], vcc
	v_or_b32_e32 v5, 27, v106
	v_max3_f32 v4, v4, v81, v80
	v_cndmask_b32_e32 v25, v218, v30, vcc
	v_cmp_le_u32_e32 vcc, v5, v103
	v_cmp_le_u32_e64 s[38:39], v101, v5
	v_max3_f32 v4, v4, v82, v83
	s_and_b64 vcc, s[38:39], vcc
	v_max3_f32 v4, v4, v28, v26
	v_cndmask_b32_e32 v23, v218, v31, vcc
	v_cmp_le_u32_e32 vcc, v105, v103
	v_cmp_le_u32_e64 s[38:39], v101, v105
	v_max3_f32 v5, v4, v25, v23
	s_and_b64 vcc, s[38:39], vcc
	v_or_b32_e32 v4, 1, v105
	v_cndmask_b32_e32 v8, v218, v32, vcc
	v_cmp_lt_u32_e32 vcc, v105, v103
	v_cmp_le_u32_e64 s[38:39], v101, v4
	s_and_b64 vcc, s[38:39], vcc
	v_cndmask_b32_e32 v4, v218, v33, vcc
	v_max3_f32 v7, v5, v8, v4
	v_or_b32_e32 v5, 2, v105
	v_cmp_le_u32_e32 vcc, v5, v103
	v_cmp_le_u32_e64 s[38:39], v101, v5
	s_and_b64 vcc, s[38:39], vcc
	v_cndmask_b32_e32 v5, v218, v34, vcc
	v_cmp_le_u32_e32 vcc, v6, v103
	v_cmp_le_u32_e64 s[38:39], v101, v6
	s_and_b64 vcc, s[38:39], vcc
	v_cndmask_b32_e32 v6, v218, v35, vcc
	v_max3_f32 v10, v7, v5, v6
	v_or_b32_e32 v7, 8, v105
	v_cmp_le_u32_e32 vcc, v7, v103
	v_cmp_le_u32_e64 s[38:39], v101, v7
	s_and_b64 vcc, s[38:39], vcc
	v_cndmask_b32_e32 v7, v218, v36, vcc
	v_cmp_le_u32_e32 vcc, v9, v103
	v_cmp_le_u32_e64 s[38:39], v101, v9
	s_and_b64 vcc, s[38:39], vcc
	v_cndmask_b32_e32 v9, v218, v37, vcc
	v_max3_f32 v11, v10, v7, v9
	v_or_b32_e32 v10, 10, v105
	v_cmp_le_u32_e32 vcc, v10, v103
	v_cmp_le_u32_e64 s[38:39], v101, v10
	s_and_b64 vcc, s[38:39], vcc
	v_cndmask_b32_e32 v10, v218, v38, vcc
	v_cmp_le_u32_e32 vcc, v12, v103
	v_cmp_le_u32_e64 s[38:39], v101, v12
	s_and_b64 vcc, s[38:39], vcc
	v_cndmask_b32_e32 v12, v218, v39, vcc
	v_max3_f32 v14, v11, v10, v12
	v_or_b32_e32 v11, 16, v105
	v_cmp_le_u32_e32 vcc, v11, v103
	v_cmp_le_u32_e64 s[38:39], v101, v11
	s_and_b64 vcc, s[38:39], vcc
	v_cndmask_b32_e32 v11, v218, v40, vcc
	v_cmp_le_u32_e32 vcc, v13, v103
	v_cmp_le_u32_e64 s[38:39], v101, v13
	s_and_b64 vcc, s[38:39], vcc
	v_cndmask_b32_e32 v13, v218, v41, vcc
	v_max3_f32 v16, v14, v11, v13
	v_or_b32_e32 v14, 18, v105
	v_cmp_le_u32_e32 vcc, v14, v103
	v_cmp_le_u32_e64 s[38:39], v101, v14
	s_and_b64 vcc, s[38:39], vcc
	v_or_b32_e32 v15, 19, v105
	v_cndmask_b32_e32 v14, v218, v42, vcc
	v_cmp_le_u32_e32 vcc, v15, v103
	v_cmp_le_u32_e64 s[38:39], v101, v15
	s_and_b64 vcc, s[38:39], vcc
	v_cndmask_b32_e32 v15, v218, v43, vcc
	v_max3_f32 v18, v16, v14, v15
	v_or_b32_e32 v16, 24, v105
	v_cmp_le_u32_e32 vcc, v16, v103
	v_cmp_le_u32_e64 s[38:39], v101, v16
	s_and_b64 vcc, s[38:39], vcc
	v_or_b32_e32 v17, 25, v105
	v_cndmask_b32_e32 v16, v218, v44, vcc
	v_cmp_le_u32_e32 vcc, v17, v103
	v_cmp_le_u32_e64 s[38:39], v101, v17
	s_and_b64 vcc, s[38:39], vcc
	v_cndmask_b32_e32 v17, v218, v45, vcc
	v_max3_f32 v19, v18, v16, v17
	v_or_b32_e32 v18, 26, v105
	v_cmp_le_u32_e32 vcc, v18, v103
	v_cmp_le_u32_e64 s[38:39], v101, v18
	s_and_b64 vcc, s[38:39], vcc
	v_or_b32_e32 v20, 27, v105
	v_cndmask_b32_e32 v18, v218, v46, vcc
	v_cmp_le_u32_e32 vcc, v20, v103
	v_cmp_le_u32_e64 s[38:39], v101, v20
	s_and_b64 vcc, s[38:39], vcc
	v_cndmask_b32_e32 v20, v218, v47, vcc
	v_cmp_le_u32_e32 vcc, v102, v103
	v_cmp_le_u32_e64 s[38:39], v101, v102
	s_and_b64 vcc, s[38:39], vcc
	v_or_b32_e32 v21, 1, v102
	v_max3_f32 v22, v19, v18, v20
	v_cndmask_b32_e32 v19, v218, v48, vcc
	v_cmp_lt_u32_e32 vcc, v102, v103
	v_cmp_le_u32_e64 s[38:39], v101, v21
	s_and_b64 vcc, s[38:39], vcc
	v_cndmask_b32_e32 v21, v218, v49, vcc
	v_max3_f32 v27, v22, v19, v21
	v_or_b32_e32 v22, 2, v102
	v_cmp_le_u32_e32 vcc, v22, v103
	v_cmp_le_u32_e64 s[38:39], v101, v22
	s_and_b64 vcc, s[38:39], vcc
	v_or_b32_e32 v24, 3, v102
	v_cndmask_b32_e32 v22, v218, v50, vcc
	v_cmp_le_u32_e32 vcc, v24, v103
	v_cmp_le_u32_e64 s[38:39], v101, v24
	s_and_b64 vcc, s[38:39], vcc
	v_cndmask_b32_e32 v24, v218, v51, vcc
	v_max3_f32 v30, v27, v22, v24
	v_or_b32_e32 v27, 8, v102
	v_cmp_le_u32_e32 vcc, v27, v103
	v_cmp_le_u32_e64 s[38:39], v101, v27
	s_and_b64 vcc, s[38:39], vcc
	v_or_b32_e32 v29, 9, v102
	v_cndmask_b32_e32 v27, v218, v52, vcc
	v_cmp_le_u32_e32 vcc, v29, v103
	v_cmp_le_u32_e64 s[38:39], v101, v29
	s_and_b64 vcc, s[38:39], vcc
	v_cndmask_b32_e32 v29, v218, v53, vcc
	v_max3_f32 v31, v30, v27, v29
	v_or_b32_e32 v30, 10, v102
	v_cmp_le_u32_e32 vcc, v30, v103
	v_cmp_le_u32_e64 s[38:39], v101, v30
	s_and_b64 vcc, s[38:39], vcc
	v_or_b32_e32 v32, 11, v102
	v_cndmask_b32_e32 v30, v218, v54, vcc
	v_cmp_le_u32_e32 vcc, v32, v103
	v_cmp_le_u32_e64 s[38:39], v101, v32
	s_and_b64 vcc, s[38:39], vcc
	v_cndmask_b32_e32 v32, v218, v55, vcc
	v_max3_f32 v34, v31, v30, v32
	v_or_b32_e32 v31, 16, v102
	v_cmp_le_u32_e32 vcc, v31, v103
	v_cmp_le_u32_e64 s[38:39], v101, v31
	s_and_b64 vcc, s[38:39], vcc
	v_or_b32_e32 v33, 17, v102
	v_cndmask_b32_e32 v31, v218, v56, vcc
	v_cmp_le_u32_e32 vcc, v33, v103
	v_cmp_le_u32_e64 s[38:39], v101, v33
	s_and_b64 vcc, s[38:39], vcc
	v_cndmask_b32_e32 v33, v218, v57, vcc
	v_max3_f32 v36, v34, v31, v33
	v_or_b32_e32 v34, 18, v102
	v_cmp_le_u32_e32 vcc, v34, v103
	v_cmp_le_u32_e64 s[38:39], v101, v34
	s_and_b64 vcc, s[38:39], vcc
	v_or_b32_e32 v35, 19, v102
	v_cndmask_b32_e32 v34, v218, v58, vcc
	v_cmp_le_u32_e32 vcc, v35, v103
	v_cmp_le_u32_e64 s[38:39], v101, v35
	s_and_b64 vcc, s[38:39], vcc
	v_cndmask_b32_e32 v35, v218, v59, vcc
	v_max3_f32 v38, v36, v34, v35
	v_or_b32_e32 v36, 24, v102
	v_cmp_le_u32_e32 vcc, v36, v103
	v_cmp_le_u32_e64 s[38:39], v101, v36
	s_and_b64 vcc, s[38:39], vcc
	v_or_b32_e32 v37, 25, v102
	v_cndmask_b32_e32 v36, v218, v60, vcc
	v_cmp_le_u32_e32 vcc, v37, v103
	v_cmp_le_u32_e64 s[38:39], v101, v37
	s_and_b64 vcc, s[38:39], vcc
	v_cndmask_b32_e32 v37, v218, v61, vcc
	v_max3_f32 v39, v38, v36, v37
	v_or_b32_e32 v38, 26, v102
	v_cmp_le_u32_e32 vcc, v38, v103
	v_cmp_le_u32_e64 s[38:39], v101, v38
	s_and_b64 vcc, s[38:39], vcc
	v_or_b32_e32 v40, 27, v102
	v_cndmask_b32_e32 v38, v218, v62, vcc
	v_cmp_le_u32_e32 vcc, v40, v103
	v_cmp_le_u32_e64 s[38:39], v101, v40
	s_and_b64 vcc, s[38:39], vcc
	v_lshl_or_b32 v101, s8, 5, v100
	v_cndmask_b32_e32 v47, v218, v63, vcc
	v_cmp_le_u32_e32 vcc, v101, v103
	v_max3_f32 v40, v39, v38, v47
	v_or_b32_e32 v46, 19, v101
	v_cndmask_b32_e32 v41, v218, v64, vcc
	v_cmp_lt_u32_e32 vcc, v101, v103
	v_or_b32_e32 v51, 25, v101
	v_or_b32_e32 v55, 27, v101
	v_cndmask_b32_e32 v39, v218, v65, vcc
	v_cndmask_b32_e32 v42, v41, v64, vcc
	v_max3_f32 v40, v40, v41, v39
	v_or_b32_e32 v41, 2, v101
	v_cmp_le_u32_e32 vcc, v41, v103
	v_or_b32_e32 v41, 3, v101
	v_and_b32_e32 v58, 64, v214
	v_cndmask_b32_e32 v43, v218, v66, vcc
	v_cmp_le_u32_e32 vcc, v41, v103
	v_or_b32_e32 v41, 8, v101
	v_add_u32_e32 v58, 64, v58
	v_cndmask_b32_e32 v44, v218, v67, vcc
	v_cmp_le_u32_e32 vcc, v41, v103
	v_or_b32_e32 v41, 9, v101
	v_max3_f32 v40, v40, v43, v44
	v_cndmask_b32_e32 v48, v218, v68, vcc
	v_cmp_le_u32_e32 vcc, v41, v103
	v_or_b32_e32 v41, 10, v101
	s_nop 0
	v_cndmask_b32_e32 v49, v218, v69, vcc
	v_cmp_le_u32_e32 vcc, v41, v103
	v_or_b32_e32 v41, 11, v101
	v_max3_f32 v40, v40, v48, v49
	v_cndmask_b32_e32 v52, v218, v70, vcc
	v_cmp_le_u32_e32 vcc, v41, v103
	v_or_b32_e32 v41, 17, v101
	s_nop 0
	v_cndmask_b32_e32 v53, v218, v71, vcc
	v_max3_f32 v45, v40, v52, v53
	v_or_b32_e32 v40, 16, v101
	v_cmp_le_u32_e32 vcc, v40, v103
	s_nop 1
	v_cndmask_b32_e32 v40, v218, v72, vcc
	v_cmp_le_u32_e32 vcc, v41, v103
	s_nop 1
	v_cndmask_b32_e32 v41, v218, v73, vcc
	v_max3_f32 v50, v45, v40, v41
	v_or_b32_e32 v45, 18, v101
	v_cmp_le_u32_e32 vcc, v45, v103
	s_nop 1
	v_cndmask_b32_e32 v45, v218, v74, vcc
	v_cmp_le_u32_e32 vcc, v46, v103
	s_nop 1
	v_cndmask_b32_e32 v46, v218, v75, vcc
	v_max3_f32 v54, v50, v45, v46
	v_or_b32_e32 v50, 24, v101
	v_cmp_le_u32_e32 vcc, v50, v103
	s_nop 1
	v_cndmask_b32_e32 v50, v218, v76, vcc
	v_cmp_le_u32_e32 vcc, v51, v103
	s_nop 1
	v_cndmask_b32_e32 v51, v218, v77, vcc
	v_max3_f32 v56, v54, v50, v51
	v_or_b32_e32 v54, 26, v101
	v_cmp_le_u32_e32 vcc, v54, v103
	s_nop 1
	v_cndmask_b32_e32 v54, v218, v78, vcc
	v_cmp_le_u32_e32 vcc, v55, v103
	s_nop 1
	v_cndmask_b32_e32 v55, v218, v79, vcc
	v_max3_f32 v57, v56, v54, v55
	v_xor_b32_e32 v56, 32, v214
	v_cmp_lt_i32_e32 vcc, v56, v58
	s_nop 1
	v_cndmask_b32_e32 v56, v214, v56, vcc
	v_lshlrev_b32_e32 v56, 2, v56
	ds_bpermute_b32 v58, v56, v57
	s_waitcnt lgkmcnt(0)
	v_max_f32_e32 v58, v58, v58
	v_max_f32_e32 v100, v57, v58
	v_sub_f32_e32 v0, v0, v100
	v_exp_f32_e32 v0, v0
	v_sub_f32_e32 v1, v1, v100
	v_exp_f32_e32 v1, v1
	v_sub_f32_e32 v2, v2, v100
	v_exp_f32_e32 v2, v2
	v_sub_f32_e32 v3, v3, v100
	v_exp_f32_e32 v3, v3
	v_sub_f32_e32 v58, v104, v100
	v_sub_f32_e32 v59, v116, v100
	v_add_f32_e32 v57, 0, v0
	v_exp_f32_e32 v58, v58
	v_exp_f32_e32 v59, v59
	v_add_f32_e32 v57, v1, v57
	v_sub_f32_e32 v60, v117, v100
	v_sub_f32_e32 v61, v118, v100
	v_add_f32_e32 v57, v2, v57
	v_exp_f32_e32 v60, v60
	v_exp_f32_e32 v61, v61
	v_add_f32_e32 v57, v3, v57
	v_add_f32_e32 v57, v58, v57
	v_cvt_pk_bf16_f32 v0, v0, v1
	v_cvt_pk_bf16_f32 v1, v2, v3
	v_cvt_pk_bf16_f32 v2, v58, v59
	v_sub_f32_e32 v58, v98, v100
	v_add_f32_e32 v57, v59, v57
	v_exp_f32_e32 v58, v58
	v_sub_f32_e32 v59, v99, v100
	v_add_f32_e32 v57, v60, v57
	v_cvt_pk_bf16_f32 v3, v60, v61
	v_exp_f32_e32 v59, v59
	v_sub_f32_e32 v60, v96, v100
	v_add_f32_e32 v57, v61, v57
	v_exp_f32_e32 v60, v60
	v_sub_f32_e32 v61, v97, v100
	v_exp_f32_e32 v61, v61
	v_sub_f32_e32 v62, v94, v100
	v_add_f32_e32 v57, v58, v57
	v_exp_f32_e32 v62, v62
	v_sub_f32_e32 v63, v95, v100
	v_add_f32_e32 v57, v59, v57
	v_exp_f32_e32 v63, v63
	v_sub_f32_e32 v64, v92, v100
	v_add_f32_e32 v57, v60, v57
	v_exp_f32_e32 v64, v64
	v_sub_f32_e32 v65, v93, v100
	v_add_f32_e32 v57, v61, v57
	v_exp_f32_e32 v65, v65
	v_cvt_pk_bf16_f32 v96, v58, v59
	v_sub_f32_e32 v58, v88, v100
	v_add_f32_e32 v57, v62, v57
	v_exp_f32_e32 v58, v58
	v_sub_f32_e32 v59, v85, v100
	v_add_f32_e32 v57, v63, v57
	v_cvt_pk_bf16_f32 v97, v60, v61
	v_exp_f32_e32 v59, v59
	v_sub_f32_e32 v60, v89, v100
	v_add_f32_e32 v57, v64, v57
	v_exp_f32_e32 v60, v60
	v_sub_f32_e32 v61, v91, v100
	v_add_f32_e32 v57, v65, v57
	v_cvt_pk_bf16_f32 v98, v62, v63
	v_exp_f32_e32 v61, v61
	v_sub_f32_e32 v62, v86, v100
	v_add_f32_e32 v57, v58, v57
	v_exp_f32_e32 v62, v62
	v_sub_f32_e32 v63, v84, v100
	v_cvt_pk_bf16_f32 v99, v64, v65
	v_add_f32_e32 v57, v59, v57
	v_exp_f32_e32 v63, v63
	v_sub_f32_e32 v64, v87, v100
	v_add_f32_e32 v57, v60, v57
	v_exp_f32_e32 v64, v64
	v_sub_f32_e32 v65, v90, v100
	v_add_f32_e32 v57, v61, v57
	v_exp_f32_e32 v65, v65
	v_cvt_pk_bf16_f32 v92, v58, v59
	v_sub_f32_e32 v58, v81, v100
	v_add_f32_e32 v57, v62, v57
	v_exp_f32_e32 v58, v58
	v_sub_f32_e32 v59, v80, v100
	v_add_f32_e32 v57, v63, v57
	v_cvt_pk_bf16_f32 v93, v60, v61
	v_exp_f32_e32 v59, v59
	v_sub_f32_e32 v60, v82, v100
	v_add_f32_e32 v57, v64, v57
	v_exp_f32_e32 v60, v60
	v_sub_f32_e32 v61, v83, v100
	v_add_f32_e32 v57, v65, v57
	v_exp_f32_e32 v61, v61
	v_sub_f32_e32 v28, v28, v100
	v_add_f32_e32 v57, v58, v57
	v_exp_f32_e32 v28, v28
	v_sub_f32_e32 v26, v26, v100
	v_add_f32_e32 v57, v59, v57
	v_exp_f32_e32 v26, v26
	v_sub_f32_e32 v25, v25, v100
	v_add_f32_e32 v57, v60, v57
	v_exp_f32_e32 v25, v25
	v_sub_f32_e32 v23, v23, v100
	v_add_f32_e32 v57, v61, v57
	v_exp_f32_e32 v23, v23
	v_sub_f32_e32 v8, v8, v100
	v_add_f32_e32 v57, v28, v57
	v_exp_f32_e32 v8, v8
	v_sub_f32_e32 v4, v4, v100
	v_add_f32_e32 v57, v26, v57
	v_exp_f32_e32 v4, v4
	v_sub_f32_e32 v5, v5, v100
	v_add_f32_e32 v57, v25, v57
	v_exp_f32_e32 v5, v5
	v_sub_f32_e32 v6, v6, v100
	v_add_f32_e32 v57, v23, v57
	v_exp_f32_e32 v6, v6
	v_sub_f32_e32 v7, v7, v100
	v_cvt_pk_bf16_f32 v91, v25, v23
	v_add_f32_e32 v23, v8, v57
	v_exp_f32_e32 v7, v7
	v_sub_f32_e32 v9, v9, v100
	v_add_f32_e32 v23, v4, v23
	v_exp_f32_e32 v9, v9
	v_sub_f32_e32 v10, v10, v100
	v_add_f32_e32 v23, v5, v23
	v_exp_f32_e32 v10, v10
	v_sub_f32_e32 v12, v12, v100
	v_add_f32_e32 v23, v6, v23
	v_exp_f32_e32 v12, v12
	v_cvt_pk_bf16_f32 v84, v8, v4
	v_sub_f32_e32 v4, v11, v100
	v_add_f32_e32 v23, v7, v23
	v_cvt_pk_bf16_f32 v85, v5, v6
	v_exp_f32_e32 v4, v4
	v_sub_f32_e32 v6, v13, v100
	v_add_f32_e32 v23, v9, v23
	v_cvt_pk_bf16_f32 v86, v7, v9
	v_exp_f32_e32 v6, v6
	v_sub_f32_e32 v7, v14, v100
	v_add_f32_e32 v23, v10, v23
	v_exp_f32_e32 v7, v7
	v_sub_f32_e32 v8, v15, v100
	v_add_f32_e32 v23, v12, v23
	v_exp_f32_e32 v8, v8
	v_sub_f32_e32 v9, v16, v100
	v_cvt_pk_bf16_f32 v87, v10, v12
	v_add_f32_e32 v5, v4, v23
	v_exp_f32_e32 v9, v9
	v_sub_f32_e32 v10, v17, v100
	v_add_f32_e32 v5, v6, v5
	v_exp_f32_e32 v10, v10
	v_sub_f32_e32 v11, v18, v100
	v_add_f32_e32 v5, v7, v5
	v_exp_f32_e32 v11, v11
	v_sub_f32_e32 v12, v20, v100
	v_add_f32_e32 v5, v8, v5
	v_exp_f32_e32 v12, v12
	v_cvt_pk_bf16_f32 v80, v4, v6
	v_sub_f32_e32 v4, v19, v100
	v_add_f32_e32 v5, v9, v5
	v_exp_f32_e32 v4, v4
	v_sub_f32_e32 v6, v21, v100
	v_add_f32_e32 v5, v10, v5
	v_cvt_pk_bf16_f32 v81, v7, v8
	v_exp_f32_e32 v6, v6
	v_sub_f32_e32 v7, v22, v100
	v_add_f32_e32 v5, v11, v5
	v_exp_f32_e32 v7, v7
	v_sub_f32_e32 v8, v24, v100
	v_add_f32_e32 v5, v12, v5
	v_cvt_pk_bf16_f32 v82, v9, v10
	v_exp_f32_e32 v8, v8
	v_sub_f32_e32 v9, v27, v100
	v_add_f32_e32 v5, v4, v5
	v_exp_f32_e32 v9, v9
	v_sub_f32_e32 v10, v29, v100
	v_cvt_pk_bf16_f32 v83, v11, v12
	v_add_f32_e32 v5, v6, v5
	v_exp_f32_e32 v10, v10
	v_sub_f32_e32 v11, v30, v100
	v_add_f32_e32 v5, v7, v5
	v_exp_f32_e32 v11, v11
	v_sub_f32_e32 v12, v32, v100
	v_add_f32_e32 v5, v8, v5
	v_exp_f32_e32 v12, v12
	v_cvt_pk_bf16_f32 v76, v4, v6
	v_sub_f32_e32 v4, v31, v100
	v_add_f32_e32 v5, v9, v5
	v_exp_f32_e32 v4, v4
	v_sub_f32_e32 v6, v33, v100
	v_add_f32_e32 v5, v10, v5
	v_cvt_pk_bf16_f32 v77, v7, v8
	v_exp_f32_e32 v6, v6
	v_sub_f32_e32 v7, v34, v100
	v_add_f32_e32 v5, v11, v5
	v_exp_f32_e32 v7, v7
	v_sub_f32_e32 v8, v35, v100
	v_add_f32_e32 v5, v12, v5
	v_cvt_pk_bf16_f32 v78, v9, v10
	v_exp_f32_e32 v8, v8
	v_sub_f32_e32 v9, v36, v100
	v_add_f32_e32 v5, v4, v5
	v_exp_f32_e32 v9, v9
	v_sub_f32_e32 v10, v37, v100
	v_cvt_pk_bf16_f32 v79, v11, v12
	v_add_f32_e32 v5, v6, v5
	v_exp_f32_e32 v10, v10
	v_sub_f32_e32 v11, v38, v100
	v_add_f32_e32 v5, v7, v5
	v_exp_f32_e32 v11, v11
	v_sub_f32_e32 v12, v47, v100
	v_add_f32_e32 v5, v8, v5
	v_exp_f32_e32 v12, v12
	v_cvt_pk_bf16_f32 v72, v4, v6
	v_sub_f32_e32 v4, v42, v100
	v_add_f32_e32 v5, v9, v5
	v_exp_f32_e32 v4, v4
	v_sub_f32_e32 v6, v39, v100
	v_add_f32_e32 v5, v10, v5
	v_cvt_pk_bf16_f32 v73, v7, v8
	v_exp_f32_e32 v6, v6
	v_sub_f32_e32 v7, v43, v100
	v_add_f32_e32 v5, v11, v5
	v_exp_f32_e32 v7, v7
	v_sub_f32_e32 v8, v44, v100
	v_add_f32_e32 v5, v12, v5
	v_cvt_pk_bf16_f32 v74, v9, v10
	v_exp_f32_e32 v8, v8
	v_sub_f32_e32 v9, v48, v100
	v_add_f32_e32 v5, v4, v5
	v_exp_f32_e32 v9, v9
	v_sub_f32_e32 v10, v49, v100
	v_cvt_pk_bf16_f32 v75, v11, v12
	v_add_f32_e32 v5, v6, v5
	v_exp_f32_e32 v10, v10
	v_sub_f32_e32 v11, v52, v100
	v_add_f32_e32 v5, v7, v5
	v_exp_f32_e32 v11, v11
	v_sub_f32_e32 v12, v53, v100
	v_add_f32_e32 v5, v8, v5
	v_exp_f32_e32 v12, v12
	v_cvt_pk_bf16_f32 v68, v4, v6
	v_sub_f32_e32 v4, v40, v100
	v_add_f32_e32 v5, v9, v5
	v_exp_f32_e32 v4, v4
	v_sub_f32_e32 v6, v41, v100
	v_add_f32_e32 v5, v10, v5
	v_cvt_pk_bf16_f32 v69, v7, v8
	v_exp_f32_e32 v6, v6
	v_sub_f32_e32 v7, v45, v100
	v_add_f32_e32 v5, v11, v5
	v_exp_f32_e32 v7, v7
	v_sub_f32_e32 v8, v46, v100
	v_add_f32_e32 v5, v12, v5
	v_cvt_pk_bf16_f32 v70, v9, v10
	v_exp_f32_e32 v8, v8
	v_sub_f32_e32 v9, v50, v100
	v_sub_f32_e32 v10, v51, v100
	v_add_f32_e32 v5, v4, v5
	v_exp_f32_e32 v9, v9
	v_exp_f32_e32 v10, v10
	v_add_f32_e32 v5, v6, v5
	v_add_f32_e32 v5, v7, v5
	v_cvt_pk_bf16_f32 v95, v64, v65
	v_cvt_pk_bf16_f32 v71, v11, v12
	v_add_f32_e32 v5, v8, v5
	v_sub_f32_e32 v11, v54, v100
	v_cvt_pk_bf16_f32 v64, v4, v6
	v_lshlrev_b32_e32 v4, 1, v115
	v_add_f32_e32 v5, v9, v5
	v_exp_f32_e32 v11, v11
	v_sub_f32_e32 v12, v55, v100
	v_cvt_pk_bf16_f32 v66, v9, v10
	v_and_b32_e32 v9, 32, v4
	v_lshlrev_b32_e32 v4, 3, v115
	v_exp_f32_e32 v12, v12
	v_bfe_u32 v116, v115, 2, 2
	v_and_b32_e32 v4, 24, v4
	v_cvt_pk_bf16_f32 v65, v7, v8
	v_lshlrev_b32_e32 v8, 6, v116
	v_add_u32_e32 v115, s10, v4
	v_or_b32_e32 v4, v107, v116
	v_add_f32_e32 v5, v10, v5
	v_or_b32_e32 v118, v8, v9
	v_lshl_add_u32 v10, v4, 8, v115
	v_add_f32_e32 v5, v11, v5
	v_add_u32_e32 v122, v10, v118
	v_add_f32_e32 v103, v12, v5
	ds_read_b64_tr_b16 v[4:5], v122
	ds_read_b64_tr_b16 v[6:7], v122 offset:2048
	v_bitop3_b32 v107, v9, v8, 64 bitop3:0x36
	v_add_u32_e32 v124, v10, v107
	v_cvt_pk_bf16_f32 v94, v62, v63
	v_cvt_pk_bf16_f32 v88, v58, v59
	v_cvt_pk_bf16_f32 v89, v60, v61
	ds_bpermute_b32 v104, v56, v103
	s_waitcnt lgkmcnt(1)
	v_mfma_f32_32x32x16_bf16 v[48:63], v[4:7], v[0:3], 0
	ds_read_b64_tr_b16 v[4:5], v124
	ds_read_b64_tr_b16 v[6:7], v124 offset:2048
	v_bitop3_b32 v117, v9, v8, s4 bitop3:0x36
	v_add_u32_e32 v125, v10, v117
	s_movk_i32 s4, 0xc0
	v_bitop3_b32 v119, v9, v8, s4 bitop3:0x36
	v_add_u32_e32 v126, v10, v119
	v_cvt_pk_bf16_f32 v90, v28, v26
	s_waitcnt lgkmcnt(0)
	v_mfma_f32_32x32x16_bf16 v[32:47], v[4:7], v[0:3], 0
	ds_read_b64_tr_b16 v[4:5], v125
	ds_read_b64_tr_b16 v[6:7], v125 offset:2048
	v_cvt_pk_bf16_f32 v67, v11, v12
	s_waitcnt lgkmcnt(0)
	v_mfma_f32_32x32x16_bf16 v[16:31], v[4:7], v[0:3], 0
	ds_read_b64_tr_b16 v[4:5], v126
	ds_read_b64_tr_b16 v[6:7], v126 offset:2048
	ds_read_b64_tr_b16 v[120:121], v122 offset:4096
	ds_read_b64_tr_b16 v[122:123], v122 offset:6144
	s_waitcnt lgkmcnt(0)
	v_mfma_f32_32x32x16_bf16 v[48:63], v[120:123], v[96:99], v[48:63]
	ds_read_b64_tr_b16 v[120:121], v124 offset:4096
	ds_read_b64_tr_b16 v[122:123], v124 offset:6144
	s_waitcnt lgkmcnt(0)
	v_mfma_f32_32x32x16_bf16 v[32:47], v[120:123], v[96:99], v[32:47]
	ds_read_b64_tr_b16 v[120:121], v125 offset:4096
	ds_read_b64_tr_b16 v[122:123], v125 offset:6144
	v_mfma_f32_32x32x16_bf16 v[0:15], v[4:7], v[0:3], 0
	s_waitcnt lgkmcnt(0)
	v_mfma_f32_32x32x16_bf16 v[16:31], v[120:123], v[96:99], v[16:31]
	ds_read_b64_tr_b16 v[120:121], v126 offset:4096
	ds_read_b64_tr_b16 v[122:123], v126 offset:6144
	s_waitcnt lgkmcnt(0)
	v_mfma_f32_32x32x16_bf16 v[0:15], v[120:123], v[96:99], v[0:15]
	v_or_b32_e32 v96, v106, v116
	v_lshl_add_u32 v106, v96, 8, v115
	v_add_u32_e32 v120, v106, v118
	ds_read_b64_tr_b16 v[96:97], v120
	ds_read_b64_tr_b16 v[98:99], v120 offset:2048
	v_add_u32_e32 v121, v106, v107
	v_add_u32_e32 v122, v106, v117
	v_add_u32_e32 v106, v106, v119
	s_waitcnt lgkmcnt(0)
	v_mfma_f32_32x32x16_bf16 v[48:63], v[96:99], v[92:95], v[48:63]
	ds_read_b64_tr_b16 v[96:97], v121
	ds_read_b64_tr_b16 v[98:99], v121 offset:2048
	s_waitcnt lgkmcnt(0)
	v_mfma_f32_32x32x16_bf16 v[32:47], v[96:99], v[92:95], v[32:47]
	ds_read_b64_tr_b16 v[96:97], v122
	ds_read_b64_tr_b16 v[98:99], v122 offset:2048
	s_waitcnt lgkmcnt(0)
	v_mfma_f32_32x32x16_bf16 v[16:31], v[96:99], v[92:95], v[16:31]
	ds_read_b64_tr_b16 v[96:97], v106
	ds_read_b64_tr_b16 v[98:99], v106 offset:2048
	s_waitcnt lgkmcnt(0)
	v_mfma_f32_32x32x16_bf16 v[0:15], v[96:99], v[92:95], v[0:15]
	ds_read_b64_tr_b16 v[92:93], v120 offset:4096
	ds_read_b64_tr_b16 v[94:95], v120 offset:6144
	s_waitcnt lgkmcnt(0)
	v_mfma_f32_32x32x16_bf16 v[48:63], v[92:95], v[88:91], v[48:63]
	ds_read_b64_tr_b16 v[92:93], v121 offset:4096
	ds_read_b64_tr_b16 v[94:95], v121 offset:6144
	s_waitcnt lgkmcnt(0)
	v_mfma_f32_32x32x16_bf16 v[32:47], v[92:95], v[88:91], v[32:47]
	ds_read_b64_tr_b16 v[92:93], v122 offset:4096
	ds_read_b64_tr_b16 v[94:95], v122 offset:6144
	s_waitcnt lgkmcnt(0)
	v_mfma_f32_32x32x16_bf16 v[16:31], v[92:95], v[88:91], v[16:31]
	ds_read_b64_tr_b16 v[92:93], v106 offset:4096
	ds_read_b64_tr_b16 v[94:95], v106 offset:6144
	s_waitcnt lgkmcnt(0)
	v_mfma_f32_32x32x16_bf16 v[0:15], v[92:95], v[88:91], v[0:15]
	v_or_b32_e32 v88, v105, v116
	v_lshl_add_u32 v92, v88, 8, v115
	v_add_u32_e32 v93, v92, v118
	ds_read_b64_tr_b16 v[88:89], v93
	ds_read_b64_tr_b16 v[90:91], v93 offset:2048
	v_add_u32_e32 v94, v92, v107
	v_add_u32_e32 v95, v92, v117
	v_add_u32_e32 v92, v92, v119
	s_waitcnt lgkmcnt(0)
	v_mfma_f32_32x32x16_bf16 v[48:63], v[88:91], v[84:87], v[48:63]
	ds_read_b64_tr_b16 v[88:89], v94
	ds_read_b64_tr_b16 v[90:91], v94 offset:2048
	s_waitcnt lgkmcnt(0)
	v_mfma_f32_32x32x16_bf16 v[32:47], v[88:91], v[84:87], v[32:47]
	ds_read_b64_tr_b16 v[88:89], v95
	ds_read_b64_tr_b16 v[90:91], v95 offset:2048
	s_waitcnt lgkmcnt(0)
	v_mfma_f32_32x32x16_bf16 v[16:31], v[88:91], v[84:87], v[16:31]
	ds_read_b64_tr_b16 v[88:89], v92
	ds_read_b64_tr_b16 v[90:91], v92 offset:2048
	s_waitcnt lgkmcnt(0)
	v_mfma_f32_32x32x16_bf16 v[0:15], v[88:91], v[84:87], v[0:15]
	ds_read_b64_tr_b16 v[84:85], v93 offset:4096
	ds_read_b64_tr_b16 v[86:87], v93 offset:6144
	s_waitcnt lgkmcnt(0)
	v_mfma_f32_32x32x16_bf16 v[48:63], v[84:87], v[80:83], v[48:63]
	ds_read_b64_tr_b16 v[84:85], v94 offset:4096
	ds_read_b64_tr_b16 v[86:87], v94 offset:6144
	s_waitcnt lgkmcnt(0)
	v_mfma_f32_32x32x16_bf16 v[32:47], v[84:87], v[80:83], v[32:47]
	ds_read_b64_tr_b16 v[84:85], v95 offset:4096
	ds_read_b64_tr_b16 v[86:87], v95 offset:6144
	s_waitcnt lgkmcnt(0)
	v_mfma_f32_32x32x16_bf16 v[16:31], v[84:87], v[80:83], v[16:31]
	ds_read_b64_tr_b16 v[84:85], v92 offset:4096
	ds_read_b64_tr_b16 v[86:87], v92 offset:6144
	s_waitcnt lgkmcnt(0)
	v_mfma_f32_32x32x16_bf16 v[0:15], v[84:87], v[80:83], v[0:15]
	v_or_b32_e32 v80, v102, v116
	v_lshl_add_u32 v84, v80, 8, v115
	v_add_u32_e32 v85, v84, v118
	ds_read_b64_tr_b16 v[80:81], v85
	ds_read_b64_tr_b16 v[82:83], v85 offset:2048
	v_add_u32_e32 v86, v84, v107
	v_add_u32_e32 v87, v84, v117
	v_add_u32_e32 v84, v84, v119
	s_waitcnt lgkmcnt(0)
	v_mfma_f32_32x32x16_bf16 v[48:63], v[80:83], v[76:79], v[48:63]
	ds_read_b64_tr_b16 v[80:81], v86
	ds_read_b64_tr_b16 v[82:83], v86 offset:2048
	s_waitcnt lgkmcnt(0)
	v_mfma_f32_32x32x16_bf16 v[32:47], v[80:83], v[76:79], v[32:47]
	ds_read_b64_tr_b16 v[80:81], v87
	ds_read_b64_tr_b16 v[82:83], v87 offset:2048
	s_waitcnt lgkmcnt(0)
	v_mfma_f32_32x32x16_bf16 v[16:31], v[80:83], v[76:79], v[16:31]
	ds_read_b64_tr_b16 v[80:81], v84
	ds_read_b64_tr_b16 v[82:83], v84 offset:2048
	s_waitcnt lgkmcnt(0)
	v_mfma_f32_32x32x16_bf16 v[0:15], v[80:83], v[76:79], v[0:15]
	ds_read_b64_tr_b16 v[76:77], v85 offset:4096
	ds_read_b64_tr_b16 v[78:79], v85 offset:6144
	s_waitcnt lgkmcnt(0)
	v_mfma_f32_32x32x16_bf16 v[48:63], v[76:79], v[72:75], v[48:63]
	ds_read_b64_tr_b16 v[76:77], v86 offset:4096
	ds_read_b64_tr_b16 v[78:79], v86 offset:6144
	s_waitcnt lgkmcnt(0)
	v_mfma_f32_32x32x16_bf16 v[32:47], v[76:79], v[72:75], v[32:47]
	ds_read_b64_tr_b16 v[76:77], v87 offset:4096
	ds_read_b64_tr_b16 v[78:79], v87 offset:6144
	s_waitcnt lgkmcnt(0)
	v_mfma_f32_32x32x16_bf16 v[16:31], v[76:79], v[72:75], v[16:31]
	ds_read_b64_tr_b16 v[76:77], v84 offset:4096
	ds_read_b64_tr_b16 v[78:79], v84 offset:6144
	s_waitcnt lgkmcnt(0)
	v_mfma_f32_32x32x16_bf16 v[0:15], v[76:79], v[72:75], v[0:15]
	v_or_b32_e32 v72, v101, v116
	v_lshl_add_u32 v76, v72, 8, v115
	v_add_u32_e32 v77, v76, v118
	ds_read_b64_tr_b16 v[72:73], v77
	ds_read_b64_tr_b16 v[74:75], v77 offset:2048
	v_add_u32_e32 v78, v76, v107
	v_add_u32_e32 v79, v76, v117
	v_add_u32_e32 v76, v76, v119
	s_waitcnt lgkmcnt(0)
	v_mfma_f32_32x32x16_bf16 v[48:63], v[72:75], v[68:71], v[48:63]
	ds_read_b64_tr_b16 v[72:73], v78
	ds_read_b64_tr_b16 v[74:75], v78 offset:2048
	s_waitcnt lgkmcnt(0)
	v_mfma_f32_32x32x16_bf16 v[32:47], v[72:75], v[68:71], v[32:47]
	ds_read_b64_tr_b16 v[72:73], v79
	ds_read_b64_tr_b16 v[74:75], v79 offset:2048
	s_waitcnt lgkmcnt(0)
	v_mfma_f32_32x32x16_bf16 v[16:31], v[72:75], v[68:71], v[16:31]
	ds_read_b64_tr_b16 v[72:73], v76
	ds_read_b64_tr_b16 v[74:75], v76 offset:2048
	s_waitcnt lgkmcnt(0)
	v_mfma_f32_32x32x16_bf16 v[0:15], v[72:75], v[68:71], v[0:15]
	ds_read_b64_tr_b16 v[68:69], v77 offset:4096
	ds_read_b64_tr_b16 v[70:71], v77 offset:6144
	s_waitcnt lgkmcnt(0)
	v_mfma_f32_32x32x16_bf16 v[48:63], v[68:71], v[64:67], v[48:63]
	ds_read_b64_tr_b16 v[68:69], v78 offset:4096
	ds_read_b64_tr_b16 v[70:71], v78 offset:6144
	s_waitcnt lgkmcnt(0)
	v_mfma_f32_32x32x16_bf16 v[32:47], v[68:71], v[64:67], v[32:47]
	ds_read_b64_tr_b16 v[68:69], v79 offset:4096
	ds_read_b64_tr_b16 v[70:71], v79 offset:6144
	s_waitcnt lgkmcnt(0)
	v_mfma_f32_32x32x16_bf16 v[16:31], v[68:71], v[64:67], v[16:31]
	ds_read_b64_tr_b16 v[68:69], v76 offset:4096
	ds_read_b64_tr_b16 v[70:71], v76 offset:6144
	s_waitcnt lgkmcnt(0)
	v_mfma_f32_32x32x16_bf16 v[0:15], v[68:71], v[64:67], v[0:15]
	v_add_f32_e32 v64, v103, v104
	v_div_scale_f32 v65, s[4:5], v64, v64, 1.0
	v_rcp_f32_e32 v66, v65
	s_nop 0
	v_fma_f32 v67, -v65, v66, 1.0
	v_fmac_f32_e32 v66, v67, v66
	v_div_scale_f32 v67, vcc, 1.0, v64, 1.0
	v_mul_f32_e32 v68, v67, v66
	v_fma_f32 v69, -v65, v68, v67
	v_fmac_f32_e32 v68, v69, v66
	v_fma_f32 v65, -v65, v68, v67
	v_div_fmas_f32 v65, v65, v66, v68
	v_div_fixup_f32 v66, v65, v64, 1.0
	v_pk_mul_f32 v[48:49], v[48:49], v[66:67] op_sel_hi:[1,0]
	v_pk_mul_f32 v[50:51], v[50:51], v[66:67] op_sel_hi:[1,0]
	v_pk_mul_f32 v[32:33], v[32:33], v[66:67] op_sel_hi:[1,0]
	v_pk_mul_f32 v[34:35], v[34:35], v[66:67] op_sel_hi:[1,0]
	v_pk_mul_f32 v[16:17], v[66:67], v[16:17] op_sel_hi:[0,1]
	v_pk_mul_f32 v[18:19], v[66:67], v[18:19] op_sel_hi:[0,1]
	v_pk_mul_f32 v[0:1], v[66:67], v[0:1] op_sel_hi:[0,1]
	v_pk_mul_f32 v[2:3], v[66:67], v[2:3] op_sel_hi:[0,1]
	v_lshl_add_u64 v[68:69], v[110:111], 0, v[112:113]
	v_cvt_pk_bf16_f32 v48, v48, v49
	v_cvt_pk_bf16_f32 v49, v50, v51
	v_cvt_pk_bf16_f32 v32, v32, v33
	v_cvt_pk_bf16_f32 v33, v34, v35
	v_cvt_pk_bf16_f32 v16, v16, v17
	v_cvt_pk_bf16_f32 v17, v18, v19
	v_cvt_pk_bf16_f32 v0, v0, v1
	v_cvt_pk_bf16_f32 v1, v2, v3
	global_store_dwordx2 v[68:69], v[48:49], off
	v_pk_mul_f32 v[48:49], v[52:53], v[66:67] op_sel_hi:[1,0]
	v_pk_mul_f32 v[50:51], v[54:55], v[66:67] op_sel_hi:[1,0]
	global_store_dwordx2 v[68:69], v[32:33], off offset:64
	v_pk_mul_f32 v[32:33], v[36:37], v[66:67] op_sel_hi:[1,0]
	v_pk_mul_f32 v[34:35], v[38:39], v[66:67] op_sel_hi:[1,0]
	global_store_dwordx2 v[68:69], v[16:17], off offset:128
	v_pk_mul_f32 v[16:17], v[66:67], v[20:21] op_sel_hi:[0,1]
	v_pk_mul_f32 v[18:19], v[66:67], v[22:23] op_sel_hi:[0,1]
	global_store_dwordx2 v[68:69], v[0:1], off offset:192
	v_pk_mul_f32 v[0:1], v[66:67], v[4:5] op_sel_hi:[0,1]
	v_pk_mul_f32 v[2:3], v[66:67], v[6:7] op_sel_hi:[0,1]
	v_cvt_pk_bf16_f32 v48, v48, v49
	v_cvt_pk_bf16_f32 v49, v50, v51
	v_cvt_pk_bf16_f32 v32, v32, v33
	v_cvt_pk_bf16_f32 v33, v34, v35
	v_cvt_pk_bf16_f32 v16, v16, v17
	v_cvt_pk_bf16_f32 v17, v18, v19
	v_cvt_pk_bf16_f32 v0, v0, v1
	v_cvt_pk_bf16_f32 v1, v2, v3
	global_store_dwordx2 v[68:69], v[48:49], off offset:16
	v_pk_mul_f32 v[48:49], v[56:57], v[66:67] op_sel_hi:[1,0]
	v_pk_mul_f32 v[50:51], v[58:59], v[66:67] op_sel_hi:[1,0]
	global_store_dwordx2 v[68:69], v[32:33], off offset:80
	v_pk_mul_f32 v[32:33], v[40:41], v[66:67] op_sel_hi:[1,0]
	v_pk_mul_f32 v[34:35], v[42:43], v[66:67] op_sel_hi:[1,0]
	global_store_dwordx2 v[68:69], v[16:17], off offset:144
	v_pk_mul_f32 v[16:17], v[66:67], v[24:25] op_sel_hi:[0,1]
	v_pk_mul_f32 v[18:19], v[66:67], v[26:27] op_sel_hi:[0,1]
	global_store_dwordx2 v[68:69], v[0:1], off offset:208
	v_pk_mul_f32 v[0:1], v[66:67], v[8:9] op_sel_hi:[0,1]
	v_pk_mul_f32 v[2:3], v[66:67], v[10:11] op_sel_hi:[0,1]
	v_cvt_pk_bf16_f32 v48, v48, v49
	v_cvt_pk_bf16_f32 v49, v50, v51
	v_cvt_pk_bf16_f32 v32, v32, v33
	v_cvt_pk_bf16_f32 v33, v34, v35
	v_cvt_pk_bf16_f32 v16, v16, v17
	v_cvt_pk_bf16_f32 v17, v18, v19
	v_cvt_pk_bf16_f32 v0, v0, v1
	v_cvt_pk_bf16_f32 v1, v2, v3
	global_store_dwordx2 v[68:69], v[48:49], off offset:32
	v_pk_mul_f32 v[48:49], v[60:61], v[66:67] op_sel_hi:[1,0]
	v_pk_mul_f32 v[50:51], v[62:63], v[66:67] op_sel_hi:[1,0]
	global_store_dwordx2 v[68:69], v[32:33], off offset:96
	v_pk_mul_f32 v[32:33], v[44:45], v[66:67] op_sel_hi:[1,0]
	v_pk_mul_f32 v[34:35], v[46:47], v[66:67] op_sel_hi:[1,0]
	global_store_dwordx2 v[68:69], v[16:17], off offset:160
	v_pk_mul_f32 v[16:17], v[66:67], v[28:29] op_sel_hi:[0,1]
	v_pk_mul_f32 v[18:19], v[66:67], v[30:31] op_sel_hi:[0,1]
	global_store_dwordx2 v[68:69], v[0:1], off offset:224
	v_pk_mul_f32 v[0:1], v[66:67], v[12:13] op_sel_hi:[0,1]
	v_pk_mul_f32 v[2:3], v[66:67], v[14:15] op_sel_hi:[0,1]
	v_cvt_pk_bf16_f32 v48, v48, v49
	v_cvt_pk_bf16_f32 v49, v50, v51
	v_cvt_pk_bf16_f32 v32, v32, v33
	v_cvt_pk_bf16_f32 v33, v34, v35
	v_cvt_pk_bf16_f32 v16, v16, v17
	v_cvt_pk_bf16_f32 v17, v18, v19
	v_cvt_pk_bf16_f32 v0, v0, v1
	v_cvt_pk_bf16_f32 v1, v2, v3
	v_cmp_eq_u32_e32 vcc, 0, v114
	global_store_dwordx2 v[68:69], v[48:49], off offset:48
	global_store_dwordx2 v[68:69], v[32:33], off offset:112
	global_store_dwordx2 v[68:69], v[16:17], off offset:176
	global_store_dwordx2 v[68:69], v[0:1], off offset:240
	s_and_saveexec_b64 s[4:5], vcc
	s_cbranch_execz .LBB0_578
	v_log_f32_e32 v2, v64
	v_readlane_b32 s6, v240, 45
	v_lshlrev_b64 v[0:1], 5, v[108:109]
	v_readlane_b32 s7, v240, 46
	s_lshl_b32 s22, s1, 2
	v_add_f32_e32 v2, v100, v2
	v_lshl_add_u64 v[0:1], s[6:7], 0, v[0:1]
	v_lshl_add_u64 v[0:1], v[0:1], 0, s[22:23]
	global_store_dword v[0:1], v2, off
	s_branch .LBB0_578

.LBB0_823:
	s_or_b64 exec, exec, s[10:11]
	s_barrier
	s_and_saveexec_b64 s[88:89], s[8:9]
	s_cbranch_execz .LBB0_808
	v_lshl_or_b32 v6, s0, 4, v15
	v_lshrrev_b32_e32 v2, 2, v14
	v_and_b32_e32 v17, 4, v2
	v_ashrrev_i32_e32 v7, 31, v6
	v_lshlrev_b64 v[2:3], 2, v[6:7]
	v_mul_u32_u24_e32 v7, 0x7800, v17
	v_lshl_add_u64 v[4:5], s[4:5], 0, v[2:3]
	v_lshlrev_b32_e32 v128, 2, v7
	v_lshl_add_u64 v[4:5], v[4:5], 0, v[128:129]
	v_lshl_add_u64 v[2:3], s[6:7], 0, v[2:3]
	v_lshl_add_u64 v[2:3], v[2:3], 0, v[128:129]
	v_lshl_add_u32 v6, v17, 11, v6
	s_mov_b32 s40, 0x2000
	s_mov_b32 s41, 0
	v_mov_b32_e32 v18, v4
	v_mov_b32_e32 v19, v5
	global_load_dword v40, v[18:19], off
	v_lshl_add_u64 v[18:19], v[18:19], 0, s[40:41]
	global_load_dword v41, v[18:19], off
	v_lshl_add_u64 v[18:19], v[18:19], 0, s[40:41]
	global_load_dword v42, v[18:19], off
	v_lshl_add_u64 v[18:19], v[18:19], 0, s[40:41]
	global_load_dword v43, v[18:19], off
	v_lshl_add_u64 v[18:19], v[18:19], 0, s[40:41]
	global_load_dword v44, v[18:19], off
	v_lshl_add_u64 v[18:19], v[18:19], 0, s[40:41]
	global_load_dword v45, v[18:19], off
	v_lshl_add_u64 v[18:19], v[18:19], 0, s[40:41]
	global_load_dword v46, v[18:19], off
	v_lshl_add_u64 v[18:19], v[18:19], 0, s[40:41]
	global_load_dword v47, v[18:19], off
	v_lshl_add_u64 v[18:19], v[18:19], 0, s[40:41]
	global_load_dword v48, v[18:19], off
	v_lshl_add_u64 v[18:19], v[18:19], 0, s[40:41]
	global_load_dword v49, v[18:19], off
	v_lshl_add_u64 v[18:19], v[18:19], 0, s[40:41]
	global_load_dword v50, v[18:19], off
	v_lshl_add_u64 v[18:19], v[18:19], 0, s[40:41]
	global_load_dword v51, v[18:19], off
	v_lshl_add_u64 v[18:19], v[18:19], 0, s[40:41]
	global_load_dword v52, v[18:19], off
	v_lshl_add_u64 v[18:19], v[18:19], 0, s[40:41]
	global_load_dword v53, v[18:19], off
	v_lshl_add_u64 v[18:19], v[18:19], 0, s[40:41]
	global_load_dword v54, v[18:19], off
	v_lshl_add_u64 v[18:19], v[18:19], 0, s[40:41]
	global_load_dword v55, v[18:19], off
	v_lshl_add_u64 v[18:19], v[18:19], 0, s[40:41]
	global_load_dword v56, v[18:19], off
	v_lshl_add_u64 v[18:19], v[18:19], 0, s[40:41]
	global_load_dword v57, v[18:19], off
	v_lshl_add_u64 v[18:19], v[18:19], 0, s[40:41]
	global_load_dword v58, v[18:19], off
	v_lshl_add_u64 v[18:19], v[18:19], 0, s[40:41]
	global_load_dword v59, v[18:19], off
	v_lshl_add_u64 v[18:19], v[18:19], 0, s[40:41]
	global_load_dword v60, v[18:19], off
	v_lshl_add_u64 v[18:19], v[18:19], 0, s[40:41]
	global_load_dword v61, v[18:19], off
	v_lshl_add_u64 v[18:19], v[18:19], 0, s[40:41]
	global_load_dword v62, v[18:19], off
	v_lshl_add_u64 v[18:19], v[18:19], 0, s[40:41]
	global_load_dword v63, v[18:19], off
	v_lshl_add_u64 v[18:19], v[18:19], 0, s[40:41]
	global_load_dword v64, v[18:19], off
	v_lshl_add_u64 v[18:19], v[18:19], 0, s[40:41]
	global_load_dword v65, v[18:19], off
	v_lshl_add_u64 v[18:19], v[18:19], 0, s[40:41]
	global_load_dword v66, v[18:19], off
	v_lshl_add_u64 v[18:19], v[18:19], 0, s[40:41]
	global_load_dword v67, v[18:19], off
	v_lshl_add_u64 v[18:19], v[18:19], 0, s[40:41]
	global_load_dword v68, v[18:19], off
	v_lshl_add_u64 v[18:19], v[18:19], 0, s[40:41]
	global_load_dword v69, v[18:19], off
	v_lshl_add_u64 v[18:19], v[18:19], 0, s[40:41]
	global_load_dword v70, v[18:19], off
	v_lshl_add_u64 v[18:19], v[18:19], 0, s[40:41]
	global_load_dword v71, v[18:19], off
	v_lshl_add_u64 v[18:19], v[18:19], 0, s[40:41]
	global_load_dword v72, v[18:19], off
	v_lshl_add_u64 v[18:19], v[18:19], 0, s[40:41]
	global_load_dword v73, v[18:19], off
	v_lshl_add_u64 v[18:19], v[18:19], 0, s[40:41]
	global_load_dword v74, v[18:19], off
	v_lshl_add_u64 v[18:19], v[18:19], 0, s[40:41]
	global_load_dword v75, v[18:19], off
	v_lshl_add_u64 v[18:19], v[18:19], 0, s[40:41]
	global_load_dword v76, v[18:19], off
	v_lshl_add_u64 v[18:19], v[18:19], 0, s[40:41]
	global_load_dword v77, v[18:19], off
	v_lshl_add_u64 v[18:19], v[18:19], 0, s[40:41]
	global_load_dword v78, v[18:19], off
	v_lshl_add_u64 v[18:19], v[18:19], 0, s[40:41]
	global_load_dword v79, v[18:19], off
	v_lshl_add_u64 v[18:19], v[18:19], 0, s[40:41]
	global_load_dword v80, v[18:19], off
	v_lshl_add_u64 v[18:19], v[18:19], 0, s[40:41]
	global_load_dword v81, v[18:19], off
	v_lshl_add_u64 v[18:19], v[18:19], 0, s[40:41]
	global_load_dword v82, v[18:19], off
	v_lshl_add_u64 v[18:19], v[18:19], 0, s[40:41]
	global_load_dword v83, v[18:19], off
	v_lshl_add_u64 v[18:19], v[18:19], 0, s[40:41]
	global_load_dword v84, v[18:19], off
	v_lshl_add_u64 v[18:19], v[18:19], 0, s[40:41]
	global_load_dword v85, v[18:19], off
	v_lshl_add_u64 v[18:19], v[18:19], 0, s[40:41]
	global_load_dword v86, v[18:19], off
	v_lshl_add_u64 v[18:19], v[18:19], 0, s[40:41]
	global_load_dword v87, v[18:19], off
	v_lshl_add_u64 v[18:19], v[18:19], 0, s[40:41]
	global_load_dword v88, v[18:19], off
	v_lshl_add_u64 v[18:19], v[18:19], 0, s[40:41]
	global_load_dword v89, v[18:19], off
	v_lshl_add_u64 v[18:19], v[18:19], 0, s[40:41]
	global_load_dword v90, v[18:19], off
	v_lshl_add_u64 v[18:19], v[18:19], 0, s[40:41]
	global_load_dword v91, v[18:19], off
	v_lshl_add_u64 v[18:19], v[18:19], 0, s[40:41]
	global_load_dword v92, v[18:19], off
	v_lshl_add_u64 v[18:19], v[18:19], 0, s[40:41]
	global_load_dword v93, v[18:19], off
	v_lshl_add_u64 v[18:19], v[18:19], 0, s[40:41]
	global_load_dword v94, v[18:19], off
	v_lshl_add_u64 v[18:19], v[18:19], 0, s[40:41]
	global_load_dword v95, v[18:19], off
	v_lshl_add_u64 v[18:19], v[18:19], 0, s[40:41]
	global_load_dword v96, v[18:19], off
	v_lshl_add_u64 v[18:19], v[18:19], 0, s[40:41]
	global_load_dword v97, v[18:19], off
	v_lshl_add_u64 v[18:19], v[18:19], 0, s[40:41]
	global_load_dword v98, v[18:19], off
	v_lshl_add_u64 v[18:19], v[18:19], 0, s[40:41]
	global_load_dword v99, v[18:19], off
	v_mul_f32_e32 v100, v8, v16
	v_mul_f32_e32 v101, v9, v13
	v_mul_f32_e32 v102, v0, v12
	v_mul_f32_e32 v103, v1, v10
	s_ashr_i32 s1, s0, 5
	s_cmp_lt_u32 s1, 3
	s_cselect_b64 s[42:43], -1, 0
	s_cmp_lt_u32 s1, 2
	s_cselect_b64 s[44:45], -1, 0
	s_cmp_lt_u32 s1, 1
	s_cselect_b64 s[46:47], -1, 0
	s_add_i32 s8, s1, 1
	s_lshl_b32 s8, s8, 23
	s_sub_i32 s8, 0x3f800000, s8
	v_readlane_b32 s12, v240, 54
	v_readlane_b32 s13, v240, 55
	v_mov_b32_e32 v20, v2
	v_mov_b32_e32 v21, v3
	s_waitcnt vmcnt(0)
	global_store_dword v[20:21], v41, off
	v_lshl_add_u64 v[20:21], v[20:21], 0, s[40:41]
	global_store_dword v[20:21], v42, off
	v_lshl_add_u64 v[20:21], v[20:21], 0, s[40:41]
	global_store_dword v[20:21], v43, off
	v_lshl_add_u64 v[20:21], v[20:21], 0, s[40:41]
	global_store_dword v[20:21], v44, off
	v_lshl_add_u64 v[20:21], v[20:21], 0, s[40:41]
	global_store_dword v[20:21], v45, off
	v_lshl_add_u64 v[20:21], v[20:21], 0, s[40:41]
	global_store_dword v[20:21], v46, off
	v_lshl_add_u64 v[20:21], v[20:21], 0, s[40:41]
	global_store_dword v[20:21], v47, off
	v_lshl_add_u64 v[20:21], v[20:21], 0, s[40:41]
	global_store_dword v[20:21], v48, off
	v_lshl_add_u64 v[20:21], v[20:21], 0, s[40:41]
	global_store_dword v[20:21], v49, off
	v_lshl_add_u64 v[20:21], v[20:21], 0, s[40:41]
	global_store_dword v[20:21], v50, off
	v_lshl_add_u64 v[20:21], v[20:21], 0, s[40:41]
	global_store_dword v[20:21], v51, off
	v_lshl_add_u64 v[20:21], v[20:21], 0, s[40:41]
	global_store_dword v[20:21], v52, off
	v_lshl_add_u64 v[20:21], v[20:21], 0, s[40:41]
	global_store_dword v[20:21], v53, off
	v_lshl_add_u64 v[20:21], v[20:21], 0, s[40:41]
	global_store_dword v[20:21], v54, off
	v_lshl_add_u64 v[20:21], v[20:21], 0, s[40:41]
	global_store_dword v[20:21], v100, off
	v_lshl_add_u64 v[20:21], v[20:21], 0, s[40:41]
	global_store_dword v[20:21], v56, off
	v_lshl_add_u64 v[20:21], v[20:21], 0, s[40:41]
	global_store_dword v[20:21], v57, off
	v_lshl_add_u64 v[20:21], v[20:21], 0, s[40:41]
	global_store_dword v[20:21], v58, off
	v_lshl_add_u64 v[20:21], v[20:21], 0, s[40:41]
	global_store_dword v[20:21], v59, off
	v_lshl_add_u64 v[20:21], v[20:21], 0, s[40:41]
	global_store_dword v[20:21], v60, off
	v_lshl_add_u64 v[20:21], v[20:21], 0, s[40:41]
	global_store_dword v[20:21], v61, off
	v_lshl_add_u64 v[20:21], v[20:21], 0, s[40:41]
	global_store_dword v[20:21], v62, off
	v_lshl_add_u64 v[20:21], v[20:21], 0, s[40:41]
	global_store_dword v[20:21], v63, off
	v_lshl_add_u64 v[20:21], v[20:21], 0, s[40:41]
	global_store_dword v[20:21], v64, off
	v_lshl_add_u64 v[20:21], v[20:21], 0, s[40:41]
	global_store_dword v[20:21], v65, off
	v_lshl_add_u64 v[20:21], v[20:21], 0, s[40:41]
	global_store_dword v[20:21], v66, off
	v_lshl_add_u64 v[20:21], v[20:21], 0, s[40:41]
	global_store_dword v[20:21], v67, off
	v_lshl_add_u64 v[20:21], v[20:21], 0, s[40:41]
	global_store_dword v[20:21], v68, off
	v_lshl_add_u64 v[20:21], v[20:21], 0, s[40:41]
	global_store_dword v[20:21], v69, off
	v_lshl_add_u64 v[20:21], v[20:21], 0, s[40:41]
	global_store_dword v[20:21], v101, off
	v_lshl_add_u64 v[20:21], v[20:21], 0, s[40:41]
	global_store_dword v[20:21], v71, off
	v_lshl_add_u64 v[20:21], v[20:21], 0, s[40:41]
	global_store_dword v[20:21], v72, off
	v_lshl_add_u64 v[20:21], v[20:21], 0, s[40:41]
	global_store_dword v[20:21], v73, off
	v_lshl_add_u64 v[20:21], v[20:21], 0, s[40:41]
	global_store_dword v[20:21], v74, off
	v_lshl_add_u64 v[20:21], v[20:21], 0, s[40:41]
	global_store_dword v[20:21], v75, off
	v_lshl_add_u64 v[20:21], v[20:21], 0, s[40:41]
	global_store_dword v[20:21], v76, off
	v_lshl_add_u64 v[20:21], v[20:21], 0, s[40:41]
	global_store_dword v[20:21], v77, off
	v_lshl_add_u64 v[20:21], v[20:21], 0, s[40:41]
	global_store_dword v[20:21], v78, off
	v_lshl_add_u64 v[20:21], v[20:21], 0, s[40:41]
	global_store_dword v[20:21], v79, off
	v_lshl_add_u64 v[20:21], v[20:21], 0, s[40:41]
	global_store_dword v[20:21], v80, off
	v_lshl_add_u64 v[20:21], v[20:21], 0, s[40:41]
	global_store_dword v[20:21], v81, off
	v_lshl_add_u64 v[20:21], v[20:21], 0, s[40:41]
	global_store_dword v[20:21], v82, off
	v_lshl_add_u64 v[20:21], v[20:21], 0, s[40:41]
	global_store_dword v[20:21], v83, off
	v_lshl_add_u64 v[20:21], v[20:21], 0, s[40:41]
	global_store_dword v[20:21], v84, off
	v_lshl_add_u64 v[20:21], v[20:21], 0, s[40:41]
	global_store_dword v[20:21], v102, off
	v_lshl_add_u64 v[20:21], v[20:21], 0, s[40:41]
	global_store_dword v[20:21], v86, off
	v_lshl_add_u64 v[20:21], v[20:21], 0, s[40:41]
	global_store_dword v[20:21], v87, off
	v_lshl_add_u64 v[20:21], v[20:21], 0, s[40:41]
	global_store_dword v[20:21], v88, off
	v_lshl_add_u64 v[20:21], v[20:21], 0, s[40:41]
	global_store_dword v[20:21], v89, off
	v_lshl_add_u64 v[20:21], v[20:21], 0, s[40:41]
	global_store_dword v[20:21], v90, off
	v_lshl_add_u64 v[20:21], v[20:21], 0, s[40:41]
	global_store_dword v[20:21], v91, off
	v_lshl_add_u64 v[20:21], v[20:21], 0, s[40:41]
	global_store_dword v[20:21], v92, off
	v_lshl_add_u64 v[20:21], v[20:21], 0, s[40:41]
	global_store_dword v[20:21], v93, off
	v_lshl_add_u64 v[20:21], v[20:21], 0, s[40:41]
	global_store_dword v[20:21], v94, off
	v_lshl_add_u64 v[20:21], v[20:21], 0, s[40:41]
	global_store_dword v[20:21], v95, off
	v_lshl_add_u64 v[20:21], v[20:21], 0, s[40:41]
	global_store_dword v[20:21], v96, off
	v_lshl_add_u64 v[20:21], v[20:21], 0, s[40:41]
	global_store_dword v[20:21], v97, off
	v_lshl_add_u64 v[20:21], v[20:21], 0, s[40:41]
	global_store_dword v[20:21], v98, off
	v_lshl_add_u64 v[20:21], v[20:21], 0, s[40:41]
	global_store_dword v[20:21], v99, off
	v_lshl_add_u64 v[20:21], v[20:21], 0, s[40:41]
	global_store_dword v[20:21], v103, off
	v_fma_f32 v104, v8, v16, v40
	v_cndmask_b32_e64 v104, v104, v100, s[42:43]
	v_add_f32_e32 v104, v104, v41
	v_cndmask_b32_e64 v104, v104, v100, s[42:43]
	v_add_f32_e32 v104, v104, v42
	v_cndmask_b32_e64 v104, v104, v100, s[42:43]
	v_add_f32_e32 v104, v104, v43
	v_cndmask_b32_e64 v104, v104, v100, s[42:43]
	v_add_f32_e32 v104, v104, v44
	v_cndmask_b32_e64 v104, v104, v100, s[42:43]
	v_add_f32_e32 v104, v104, v45
	v_cndmask_b32_e64 v104, v104, v100, s[42:43]
	v_add_f32_e32 v104, v104, v46
	v_cndmask_b32_e64 v104, v104, v100, s[42:43]
	v_add_f32_e32 v104, v104, v47
	v_cndmask_b32_e64 v104, v104, v100, s[42:43]
	v_add_f32_e32 v104, v104, v48
	v_cndmask_b32_e64 v104, v104, v100, s[44:45]
	v_add_f32_e32 v104, v104, v49
	v_cndmask_b32_e64 v104, v104, v100, s[44:45]
	v_add_f32_e32 v104, v104, v50
	v_cndmask_b32_e64 v104, v104, v100, s[44:45]
	v_add_f32_e32 v104, v104, v51
	v_cndmask_b32_e64 v104, v104, v100, s[44:45]
	v_add_f32_e32 v105, v104, v52
	v_cndmask_b32_e64 v105, v105, v104, s[46:47]
	v_add_f32_e32 v105, v105, v53
	v_cndmask_b32_e64 v104, v105, v104, s[46:47]
	v_add_f32_e32 v104, v104, v54
	v_mul_f32_e32 v104, s8, v104
	v_fma_f32 v104, -v8, v16, v104
	v_mov_b32_e32 v106, v6
	v_ashrrev_i32_e32 v107, 31, v106
	v_lshl_add_u64 v[108:109], v[106:107], 2, s[12:13]
	global_store_dword v[108:109], v104, off
	v_fma_f32 v104, v9, v13, v55
	v_cndmask_b32_e64 v104, v104, v101, s[42:43]
	v_add_f32_e32 v104, v104, v56
	v_cndmask_b32_e64 v104, v104, v101, s[42:43]
	v_add_f32_e32 v104, v104, v57
	v_cndmask_b32_e64 v104, v104, v101, s[42:43]
	v_add_f32_e32 v104, v104, v58
	v_cndmask_b32_e64 v104, v104, v101, s[42:43]
	v_add_f32_e32 v104, v104, v59
	v_cndmask_b32_e64 v104, v104, v101, s[42:43]
	v_add_f32_e32 v104, v104, v60
	v_cndmask_b32_e64 v104, v104, v101, s[42:43]
	v_add_f32_e32 v104, v104, v61
	v_cndmask_b32_e64 v104, v104, v101, s[42:43]
	v_add_f32_e32 v104, v104, v62
	v_cndmask_b32_e64 v104, v104, v101, s[42:43]
	v_add_f32_e32 v104, v104, v63
	v_cndmask_b32_e64 v104, v104, v101, s[44:45]
	v_add_f32_e32 v104, v104, v64
	v_cndmask_b32_e64 v104, v104, v101, s[44:45]
	v_add_f32_e32 v104, v104, v65
	v_cndmask_b32_e64 v104, v104, v101, s[44:45]
	v_add_f32_e32 v104, v104, v66
	v_cndmask_b32_e64 v104, v104, v101, s[44:45]
	v_add_f32_e32 v105, v104, v67
	v_cndmask_b32_e64 v105, v105, v104, s[46:47]
	v_add_f32_e32 v105, v105, v68
	v_cndmask_b32_e64 v104, v105, v104, s[46:47]
	v_add_f32_e32 v104, v104, v69
	v_mul_f32_e32 v104, s8, v104
	v_fma_f32 v104, -v9, v13, v104
	v_add_u32_e32 v106, 0x800, v6
	v_ashrrev_i32_e32 v107, 31, v106
	v_lshl_add_u64 v[108:109], v[106:107], 2, s[12:13]
	global_store_dword v[108:109], v104, off
	v_fma_f32 v104, v0, v12, v70
	v_cndmask_b32_e64 v104, v104, v102, s[42:43]
	v_add_f32_e32 v104, v104, v71
	v_cndmask_b32_e64 v104, v104, v102, s[42:43]
	v_add_f32_e32 v104, v104, v72
	v_cndmask_b32_e64 v104, v104, v102, s[42:43]
	v_add_f32_e32 v104, v104, v73
	v_cndmask_b32_e64 v104, v104, v102, s[42:43]
	v_add_f32_e32 v104, v104, v74
	v_cndmask_b32_e64 v104, v104, v102, s[42:43]
	v_add_f32_e32 v104, v104, v75
	v_cndmask_b32_e64 v104, v104, v102, s[42:43]
	v_add_f32_e32 v104, v104, v76
	v_cndmask_b32_e64 v104, v104, v102, s[42:43]
	v_add_f32_e32 v104, v104, v77
	v_cndmask_b32_e64 v104, v104, v102, s[42:43]
	v_add_f32_e32 v104, v104, v78
	v_cndmask_b32_e64 v104, v104, v102, s[44:45]
	v_add_f32_e32 v104, v104, v79
	v_cndmask_b32_e64 v104, v104, v102, s[44:45]
	v_add_f32_e32 v104, v104, v80
	v_cndmask_b32_e64 v104, v104, v102, s[44:45]
	v_add_f32_e32 v104, v104, v81
	v_cndmask_b32_e64 v104, v104, v102, s[44:45]
	v_add_f32_e32 v105, v104, v82
	v_cndmask_b32_e64 v105, v105, v104, s[46:47]
	v_add_f32_e32 v105, v105, v83
	v_cndmask_b32_e64 v104, v105, v104, s[46:47]
	v_add_f32_e32 v104, v104, v84
	v_mul_f32_e32 v104, s8, v104
	v_fma_f32 v104, -v0, v12, v104
	v_add_u32_e32 v106, 0x1000, v6
	v_ashrrev_i32_e32 v107, 31, v106
	v_lshl_add_u64 v[108:109], v[106:107], 2, s[12:13]
	global_store_dword v[108:109], v104, off
	v_fma_f32 v104, v1, v10, v85
	v_cndmask_b32_e64 v104, v104, v103, s[42:43]
	v_add_f32_e32 v104, v104, v86
	v_cndmask_b32_e64 v104, v104, v103, s[42:43]
	v_add_f32_e32 v104, v104, v87
	v_cndmask_b32_e64 v104, v104, v103, s[42:43]
	v_add_f32_e32 v104, v104, v88
	v_cndmask_b32_e64 v104, v104, v103, s[42:43]
	v_add_f32_e32 v104, v104, v89
	v_cndmask_b32_e64 v104, v104, v103, s[42:43]
	v_add_f32_e32 v104, v104, v90
	v_cndmask_b32_e64 v104, v104, v103, s[42:43]
	v_add_f32_e32 v104, v104, v91
	v_cndmask_b32_e64 v104, v104, v103, s[42:43]
	v_add_f32_e32 v104, v104, v92
	v_cndmask_b32_e64 v104, v104, v103, s[42:43]
	v_add_f32_e32 v104, v104, v93
	v_cndmask_b32_e64 v104, v104, v103, s[44:45]
	v_add_f32_e32 v104, v104, v94
	v_cndmask_b32_e64 v104, v104, v103, s[44:45]
	v_add_f32_e32 v104, v104, v95
	v_cndmask_b32_e64 v104, v104, v103, s[44:45]
	v_add_f32_e32 v104, v104, v96
	v_cndmask_b32_e64 v104, v104, v103, s[44:45]
	v_add_f32_e32 v105, v104, v97
	v_cndmask_b32_e64 v105, v105, v104, s[46:47]
	v_add_f32_e32 v105, v105, v98
	v_cndmask_b32_e64 v104, v105, v104, s[46:47]
	v_add_f32_e32 v104, v104, v99
	v_mul_f32_e32 v104, s8, v104
	v_fma_f32 v104, -v1, v10, v104
	v_add_u32_e32 v106, 0x1800, v6
	v_ashrrev_i32_e32 v107, 31, v106
	v_lshl_add_u64 v[108:109], v[106:107], 2, s[12:13]
	global_store_dword v[108:109], v104, off
	s_branch .LBB0_808
